# post phase overlapped with long-scan tail: scans publish chunk progress (write-through y/bonus stores + flag), P7-P8 grid barrier skipped, P8 pops tiles middle-out from an atomic counter and waits on
# speedup vs baseline: 1.0096x; 1.0096x over previous
; __device__ __forceinline__ uint2 pack4(f32x4 v) { uint2 u; u.x = cvt_pk_bf16(v[0], v[1]); u.y = cvt_pk_bf16(v[2], v[3]); return u; }
; #define MFMA16(a, b, c) __builtin_amdgcn_mfma_f32_16x16x32_bf16(a, b, c, 0, 0, 0)
; __device__ __forceinline__ void scan_phase(PREF p, char* smem, const int wid_u) {
;     ...
;     for (int c = 0; c < nch; ++c) {
;       {
;         const int mat = wave >> 1, mts = wave & 1;
;         const bf16_t* As = (mat & 1) ? Kt : Bt;
;         const bf16_t* Bs = (mat & 2) ? Rt : At;
;         f32x4 acc[2] = {};
; #pragma unroll
;         for (int ks = 0; ks < 2; ++ks) {
;           const bf16x8 a = ldfrag(As, 72, mts * 16, ks * 32, fr, fq);
; #pragma unroll
;           for (int nt = 0; nt < 2; ++nt) acc[nt] = MFMA16(a, ldfrag(Bs, 72, nt * 16, ks * 32, fr, fq), acc[nt]);
;         }
; #pragma unroll
;         for (int nt = 0; nt < 2; ++nt) {
;           const int tcol = nt * 16 + fr;
;           f32x4 v = acc[nt];
; #pragma unroll
;           for (int jj = 0; jj < 4; ++jj) {
;             const int srow = mts * 16 + fq * 4 + jj;
;             const bool keep = (mat & 2) ? (srow <= tcol) : (srow < tcol);
;             v[jj] = keep ? v[jj] : 0.f;
;           }
;           if (mat == 0) {
; #pragma unroll
;             for (int jj = 0; jj < 4; ++jj) Nab[(mts * 16 + fq * 4 + jj) * 32 + tcol] = v[jj];
;           } else {
;             bf16_t* dst = mat == 1 ? NakT : mat == 2 ? NbrT : NkrT;
;             *(uint2*)(dst + tcol * 40 + mts * 16 + fq * 4) = pack4(v);
;           }
;         }
;       }
;       lds_barrier();
;       if (wave == 4) {
;         const int irow = lane >> 1, hb = lane & 1, blk = lane >> 5, il = irow & 15;
;         float x[8];
; #pragma unroll
;         for (int i = 0; i < 8; ++i) x[i] = (hb * 8 + i == il) ? 1.f : 0.f;
;         const float* nb = Nab + (blk * 16) * 32 + blk * 16 + hb * 8;
;         solve16<0>(x, nb);
; #pragma unroll
;         for (int i = 0; i < 8; ++i) TT[(blk * 16 + hb * 8 + i) * 40 + blk * 16 + il] = (bf16_t)(cvt_pk_bf16(x[i], 0.f) & 0xffff);
;         if (blk == 0) *(uint4*)(T11b + il * 40 + hb * 8) = pack8(x);
.LBB0_537:
	s_lshr_b32 s44, s92, 5
	s_mul_i32 s18, s26, 0x6000000
	s_add_u32 s18, s48, s18
	s_addc_u32 s19, s49, 0
	s_add_u32 s64, s18, 0xee90000
	s_addc_u32 s65, s19, 0
	s_cmp_eq_u32 s20, 0
	s_mov_b32 s18, 0xe400
	v_lshlrev_b32_e32 v80, 2, v79
	s_cselect_b32 s18, s18, 0xf600
	v_or_b32_e32 v48, s84, v80
	s_add_i32 s20, s18, 0
	s_and_b32 s18, s90, 4
	s_add_i32 s28, 0, 0xc000
	s_add_i32 s29, 0, 0xd200
	v_cmp_lt_u32_e32 vcc, v48, v77
	s_cmp_eq_u32 s18, 0
	v_mul_u32_u24_e32 v128, 0x90, v90
	v_cndmask_b32_e64 v49, 0, 1, vcc
	v_cmp_le_u32_e32 vcc, v48, v77
	v_mul_u32_u24_e32 v69, 40, v77
	v_add_u32_e32 v138, s27, v55
	v_cndmask_b32_e64 v50, 0, 1, vcc
	s_cselect_b64 vcc, -1, 0
	v_cndmask_b32_e32 v49, v50, v49, vcc
	s_and_b64 s[18:19], vcc, exec
	v_lshlrev_b32_e32 v50, 1, v78
	s_cselect_b32 s18, s28, s29
	v_add3_u32 v129, s20, v128, v50
	s_add_i32 s20, 0, 0x2a00
	s_add_i32 s28, 0, 0x2000
	v_add_u32_e32 v51, s18, v50
	s_and_b64 s[18:19], s[22:23], exec
	s_cselect_b32 s18, s28, s20
	s_add_i32 s19, 0, 0x1000
	s_cmp_eq_u32 s25, 1
	s_cselect_b32 s18, s19, s18
	s_lshl_b32 s19, s84, 1
	s_add_i32 s18, s18, s19
	v_add_u32_e32 v52, s18, v78
	s_add_i32 s18, 0, 0x13000
	v_add_u32_e32 v131, s18, v50
	s_add_i32 s18, 0, 0x25100
	v_add_u32_e32 v53, s18, v55
	s_add_i32 s18, 0, 0x1f100
	v_add_u32_e32 v56, s18, v55
	s_add_i32 s18, 0, 0x10800
	s_add_i32 s20, 0, 0x1d100
	s_add_i32 s34, 0, 0x21100
	s_add_i32 s35, 0, 0x14400
	s_add_i32 s36, s19, 0
	v_add_u32_e32 v57, s18, v50
	s_add_i32 s18, 0, 0x11c00
	s_and_b32 s28, s90, -2
	s_cmp_eq_u32 s28, 2
	s_cselect_b64 s[28:29], -1, 0
	s_cmp_gt_i32 s90, 5
	s_cselect_b64 s[30:31], -1, 0
	s_or_b64 s[66:67], s[30:31], s[28:29]
	s_cmp_lt_u32 s90, 4
	s_cselect_b32 s28, -2, -4
	v_add3_u32 v139, s20, v55, v54
	s_add_i32 s20, 0, 0x27500
	v_add_u32_e32 v141, s20, v55
	s_add_i32 s20, 0, 0x27900
	v_add_u32_e32 v142, s20, v55
	s_add_i32 s20, 0, 0x27400
	v_add_u32_e32 v130, 0, v50
	s_add_i32 s28, s28, s90
	v_add_u32_e32 v143, s20, v55
	s_add_i32 s20, 0, 0x27200
	v_lshl_add_u32 v134, v69, 1, v130
	v_lshl_or_b32 v69, s28, 4, v77
	s_add_i32 s28, 0, 0x27300
	v_add_u32_e32 v144, s20, v55
	s_lshl_b32 s20, s89, 1
	s_add_u32 s27, s64, s20
	v_add_u32_e32 v137, s28, v55
	s_addc_u32 s28, s65, 0
	s_lshl_b32 s68, s25, 4
	v_add_u32_e32 v59, s21, v55
	v_lshl_add_u32 v68, v77, 7, 0
	v_mul_i32_i24_e32 v70, 0xffffffd0, v77
	v_add3_u32 v140, s34, v55, v54
	v_lshlrev_b32_e32 v55, 2, v77
	s_ashr_i32 s69, s68, 31
	v_add3_u32 v133, v68, v70, v50
	v_add_u32_e32 v70, s21, v55
	s_lshl_b64 s[20:21], s[68:69], 1
	s_add_u32 s20, s27, s20
	s_addc_u32 s21, s28, s21
	v_mov_b32_e32 v79, 0
	v_lshl_add_u64 v[82:83], s[20:21], 0, v[78:79]
	v_cmp_eq_u32_e64 s[20:21], 0, v89
	s_and_b64 s[70:71], s[20:21], s[22:23]
	s_lshl_b32 s20, s24, 3
	s_add_u32 s20, s48, s20
	s_addc_u32 s21, s49, 0
	s_lshl_b32 s22, s26, 2
	s_add_u32 s20, s20, s22
	v_mul_u32_u24_e32 v71, 40, v90
	s_movk_i32 s37, 0x50
	s_addc_u32 s21, s21, 0
	v_lshl_add_u32 v145, v71, 1, v130
	v_or_b32_e32 v71, s68, v77
	s_add_u32 s72, s20, 0x2890000
	v_mul_lo_u32 v84, v71, s37
	v_lshl_or_b32 v85, s40, 5, v77
	s_addc_u32 s73, s21, 0
	s_add_i32 s45, s92, -1
	v_add_u32_e32 v147, v130, v84
	v_add3_u32 v148, s35, v50, v84
	v_add3_u32 v149, s36, v84, v78
	v_add_u32_e32 v152, v131, v84
	v_mul_u32_u24_e32 v84, 40, v85
	v_or_b32_e32 v92, 2, v48
	v_add_u32_e32 v58, s18, v50
	s_add_u32 s74, s48, 0x3be90000
	v_lshlrev_b32_e32 v84, 1, v84
	v_cmp_lt_u32_e64 s[26:27], v92, v77
	s_addc_u32 s75, s49, 0
	s_add_i32 s22, 0, 0x16800
	v_add_u32_e32 v153, v57, v84
	v_add_u32_e32 v155, v58, v84
	v_cndmask_b32_e64 v84, 0, 1, s[26:27]
	v_cmp_le_u32_e64 s[26:27], v92, v77
	v_lshl_add_u32 v150, v85, 2, s22
	v_or_b32_e32 v86, 16, v85
	v_mul_u32_u24_e32 v157, 0x90, v85
	v_cndmask_b32_e64 v85, 0, 1, s[26:27]
	v_cndmask_b32_e32 v84, v85, v84, vcc
	v_or_b32_e32 v93, 3, v48
	v_and_b32_e32 v84, 1, v84
	v_cmp_lt_u32_e64 s[28:29], v93, v77
	v_mul_u32_u24_e32 v87, 40, v86
	v_cmp_eq_u32_e64 s[26:27], 1, v84
	v_cndmask_b32_e64 v84, 0, 1, s[28:29]
	v_cmp_le_u32_e64 s[28:29], v93, v77
	v_lshlrev_b32_e32 v87, 1, v87
	v_add_u32_e32 v156, v58, v87
	v_cndmask_b32_e64 v85, 0, 1, s[28:29]
	v_or_b32_e32 v58, 16, v77
	v_cndmask_b32_e32 v84, v85, v84, vcc
	v_and_b32_e32 v84, 1, v84
	v_cmp_lt_u32_e64 s[30:31], v48, v58
	v_add_u32_e32 v154, v57, v87
	s_lshl_b32 s20, s25, 5
	v_mul_u32_u24_e32 v57, 0x48, v90
	v_and_b32_e32 v49, 1, v49
	v_cmp_eq_u32_e64 s[28:29], 1, v84
	v_cndmask_b32_e64 v84, 0, 1, s[30:31]
	v_cmp_le_u32_e64 s[30:31], v48, v58
	s_movk_i32 s41, 0x90
	v_lshl_add_u32 v151, v86, 2, s22
	s_add_i32 s20, s20, 0
	v_lshlrev_b32_e32 v57, 1, v57
	v_lshl_add_u32 v164, v88, 2, s22
	v_cmp_eq_u32_e64 s[22:23], 1, v49
	v_or_b32_e32 v49, 1, v48
	v_cndmask_b32_e64 v85, 0, 1, s[30:31]
	v_mad_u32_u24 v60, v113, s37, 0
	v_mul_lo_u32 v136, v69, s37
	v_add3_u32 v161, s20, v57, v78
	v_mul_lo_u32 v57, v71, s41
	v_cndmask_b32_e32 v71, v48, v49, vcc
	v_cndmask_b32_e32 v84, v85, v84, vcc
	v_cmp_lt_u32_e64 s[36:37], v92, v58
	v_cmp_gt_u32_e64 s[24:25], v77, v71
	v_and_b32_e32 v84, 1, v84
	v_cmp_gt_u32_e64 s[34:35], v58, v71
	v_cndmask_b32_e64 v71, 0, 1, s[36:37]
	v_cmp_le_u32_e64 s[36:37], v92, v58
	v_cmp_eq_u32_e64 s[30:31], 1, v84
	v_cmp_lt_u32_e64 s[38:39], v93, v58
	v_cndmask_b32_e64 v84, 0, 1, s[36:37]
	v_cndmask_b32_e32 v71, v84, v71, vcc
	v_and_b32_e32 v71, 1, v71
	v_cmp_eq_u32_e64 s[36:37], 1, v71
	v_cndmask_b32_e64 v71, 0, 1, s[38:39]
	v_cmp_le_u32_e64 s[38:39], v93, v58
	v_lshrrev_b32_e32 v62, 1, v75
	v_lshlrev_b32_e32 v64, 3, v75
	v_cndmask_b32_e64 v58, 0, 1, s[38:39]
	v_cndmask_b32_e32 v58, v58, v71, vcc
	v_and_b32_e32 v58, 1, v58
	v_lshrrev_b32_e32 v63, 5, v88
	v_cmp_eq_u32_e64 s[38:39], 1, v58
	v_and_b32_e32 v58, 15, v62
	v_and_b32_e32 v62, 8, v64
	v_lshl_add_u32 v65, v63, 11, 0
	v_lshlrev_b32_e32 v66, 6, v63
	v_lshlrev_b32_e32 v64, 2, v62
	v_mul_i32_i24_e32 v67, 0xfffff820, v63
	v_add3_u32 v166, v65, v66, v64
	v_lshlrev_b32_e32 v64, 1, v58
	v_add3_u32 v64, v65, v67, v64
	v_mul_u32_u24_e32 v65, 0x50, v58
	v_lshlrev_b32_e32 v66, 1, v62
	v_add3_u32 v167, 0, v65, v66
	v_or_b32_e32 v65, 1, v62
	v_cmp_eq_u32_e32 vcc, v62, v58
	v_or_b32_e32 v66, 2, v62
	v_mul_u32_u24_e32 v159, 0x90, v86
	v_cndmask_b32_e64 v84, 0, 1.0, vcc
	v_cmp_eq_u32_e32 vcc, v58, v65
	v_or_b32_e32 v65, 3, v62
	s_add_i32 s47, 0, 0x16900
	v_cndmask_b32_e64 v85, 0, 1.0, vcc
	v_cmp_eq_u32_e32 vcc, v65, v58
	v_or_b32_e32 v65, 5, v62
	v_lshlrev_b32_e32 v61, 3, v89
	v_cndmask_b32_e64 v87, 0, 1.0, vcc
	v_cmp_eq_u32_e32 vcc, v66, v58
	v_or_b32_e32 v66, 4, v62
	s_cmp_gt_i32 s90, 4
	v_cndmask_b32_e64 v86, 0, 1.0, vcc
	v_cmp_eq_u32_e32 vcc, v65, v58
	v_or_b32_e32 v65, 7, v62
	s_waitcnt lgkmcnt(0)
	s_barrier
; __device__ __forceinline__ uint2 pack4(f32x4 v) { uint2 u; u.x = cvt_pk_bf16(v[0], v[1]); u.y = cvt_pk_bf16(v[2], v[3]); return u; }
; #define MFMA16(a, b, c) __builtin_amdgcn_mfma_f32_16x16x32_bf16(a, b, c, 0, 0, 0)
; __device__ __forceinline__ void scan_phase(PREF p, char* smem, const int wid_u) {
;     ...
;     for (int c = 0; c < nch; ++c) {
;       {
;         const int mat = wave >> 1, mts = wave & 1;
;         const bf16_t* As = (mat & 1) ? Kt : Bt;
;         const bf16_t* Bs = (mat & 2) ? Rt : At;
;         f32x4 acc[2] = {};
; #pragma unroll
;         for (int ks = 0; ks < 2; ++ks) {
;           const bf16x8 a = ldfrag(As, 72, mts * 16, ks * 32, fr, fq);
; #pragma unroll
;           for (int nt = 0; nt < 2; ++nt) acc[nt] = MFMA16(a, ldfrag(Bs, 72, nt * 16, ks * 32, fr, fq), acc[nt]);
;         }
; #pragma unroll
;         for (int nt = 0; nt < 2; ++nt) {
;           const int tcol = nt * 16 + fr;
;           f32x4 v = acc[nt];
; #pragma unroll
;           for (int jj = 0; jj < 4; ++jj) {
;             const int srow = mts * 16 + fq * 4 + jj;
;             const bool keep = (mat & 2) ? (srow <= tcol) : (srow < tcol);
;             v[jj] = keep ? v[jj] : 0.f;
;           }
;           if (mat == 0) {
; #pragma unroll
;             for (int jj = 0; jj < 4; ++jj) Nab[(mts * 16 + fq * 4 + jj) * 32 + tcol] = v[jj];
;           } else {
;             bf16_t* dst = mat == 1 ? NakT : mat == 2 ? NbrT : NkrT;
;             *(uint2*)(dst + tcol * 40 + mts * 16 + fq * 4) = pack4(v);
;           }
;         }
;       }
;       lds_barrier();
;       if (wave == 4) {
;         const int irow = lane >> 1, hb = lane & 1, blk = lane >> 5, il = irow & 15;
;         float x[8];
; #pragma unroll
;         for (int i = 0; i < 8; ++i) x[i] = (hb * 8 + i == il) ? 1.f : 0.f;
;         const float* nb = Nab + (blk * 16) * 32 + blk * 16 + hb * 8;
;         solve16<0>(x, nb);
; #pragma unroll
;         for (int i = 0; i < 8; ++i) TT[(blk * 16 + hb * 8 + i) * 40 + blk * 16 + il] = (bf16_t)(cvt_pk_bf16(x[i], 0.f) & 0xffff);
;         if (blk == 0) *(uint4*)(T11b + il * 40 + hb * 8) = pack8(x);
	v_cndmask_b32_e64 v89, 0, 1.0, vcc
	v_cmp_eq_u32_e32 vcc, v66, v58
	v_cmp_gt_u32_e64 s[18:19], 32, v88
	v_add3_u32 v158, s20, v157, v78
	v_add3_u32 v160, s20, v159, v78
	v_add3_u32 v162, s47, v57, v50
	v_or_b32_e32 v50, s68, v80
	s_cselect_b64 s[20:21], -1, 0
	v_lshl_or_b32 v63, v63, 4, v62
	v_cndmask_b32_e64 v88, 0, 1.0, vcc
	v_or_b32_e32 v62, 6, v62
	v_cmp_eq_u32_e32 vcc, v65, v58
	s_lshl_b32 s40, s40, 6
	v_lshl_add_u32 v132, v78, 2, v68
	v_sub_u32_e32 v68, 0, v78
	v_add_u32_e32 v69, 0, v136
	v_mul_u32_u24_e32 v57, 0x90, v77
	v_mul_u32_u24_e32 v165, 0x50, v77
	v_add_u32_e32 v55, 0, v55
	v_lshlrev_b32_e32 v94, 7, v48
	v_lshlrev_b32_e32 v95, 7, v49
	v_lshlrev_b32_e32 v96, 7, v92
	v_lshlrev_b32_e32 v97, 7, v93
	v_cndmask_b32_e64 v91, 0, 1.0, vcc
	v_cmp_eq_u32_e32 vcc, v62, v58
	v_mul_u32_u24_e32 v58, 0x50, v63
	v_lshlrev_b32_e32 v48, 8, v48
	v_lshlrev_b32_e32 v49, 8, v49
	v_lshlrev_b32_e32 v62, 8, v92
	v_lshlrev_b32_e32 v63, 8, v93
	s_add_i32 s47, s47, s40
	v_lshlrev_b32_e32 v65, 1, v77
	v_mul_lo_u32 v50, v50, s41
	s_movk_i32 s76, 0xec00
	v_sub_u32_e32 v135, v133, v78
	v_add_u32_e32 v163, 0xffffff00, v115
	v_cndmask_b32_e64 v90, 0, 1.0, vcc
	s_lshl_b32 s46, s90, 12
	v_add3_u32 v168, s47, v65, v50
	s_sub_i32 s47, 0, s84
	v_sub_u32_e32 v169, s92, v77
	v_sub_u32_e32 v170, s92, v113
	s_sub_i32 s87, 0, s44
	v_add_u32_e32 v171, v51, v57
	v_add_u32_e32 v172, v60, v61
	v_add_u32_e32 v173, v69, v78
	v_add_u32_e32 v174, v64, v58
	v_add_u32_e32 v175, v133, v68
	v_mov_b32_e32 v176, 0x260
	v_add_u32_e32 v177, v53, v54
	v_add_u32_e32 v178, v56, v54
	s_movk_i32 s88, 0xa00
	s_mov_b32 s77, -1
	s_mov_b64 s[78:79], 0x1400
	v_add_u32_e32 v179, v59, v54
	v_add_u32_e32 v180, v52, v165
	v_add_u32_e32 v181, v55, v94
	v_add_u32_e32 v182, v55, v95
	v_add_u32_e32 v183, v55, v96
	v_add_u32_e32 v184, v55, v97
	v_add_u32_e32 v185, v70, v48
	v_add_u32_e32 v186, v70, v49
	v_add_u32_e32 v187, v70, v62
	v_add_u32_e32 v188, v70, v63
	s_mov_b32 s93, s84
	v_mov_b32_e32 v48, v79
	v_mov_b32_e32 v49, v79
	v_mov_b32_e32 v50, v79
	v_mov_b32_e32 v51, v79
	v_mov_b32_e32 v52, v79
	v_mov_b32_e32 v53, v79
	v_mov_b32_e32 v54, v79
	v_mov_b32_e32 v55, v79
	v_mov_b32_e32 v92, v79
	v_mov_b32_e32 v93, v79
	s_load_dwordx2 s[100:101], s[0:1], 0x110
	s_lshr_b32 s98, s33, 4
	s_lshl_b32 s98, s98, 8
	s_and_b32 s99, s33, 15
	s_lshl_b32 s99, s99, 2
	s_add_u32 s98, s98, s99
	s_add_u32 s98, s98, 0x3ee90440
	s_waitcnt lgkmcnt(0)
	s_add_u32 s100, s100, s98
	s_addc_u32 s101, s101, 0
	s_branch .LBB0_540

; __device__ __forceinline__ void scan_phase(PREF p, char* smem, const int wid_u) {
;     ...
;       if (c > 0) {
;         const int ip = (c - 1) * 32 + hn * 16 + fr, tp = d ? T - 1 - ip : ip;
;         *(uint2*)(yout + (size_t)(r0seq + tp) * 512 + h * 64 + mt * 16 + fq * 4) = y_def;
;       }
;       if (role == 2 && cq == 0) { const int is_ = c * 32 + th * 16 + tl, tg = d ? T - 1 - is_ : is_; P_SBON[((size_t)(r0seq + tg) * 8 + h) * 2 + d] = sb_def; }
.LBB0_581:
	v_add_u32_e32 v56, s93, v77
	v_subrev_u32_e32 v56, 32, v56
	v_add3_u32 v57, s47, v169, 31
	v_cndmask_b32_e64 v56, v57, v56, s[2:3]
	v_add_u32_e32 v56, s91, v56
	v_ashrrev_i32_e32 v57, 31, v56
	v_lshlrev_b64 v[56:57], 10, v[56:57]
	v_lshl_add_u64 v[56:57], v[82:83], 0, v[56:57]
	global_store_dwordx2 v[56:57], v[92:93], off sc0 sc1
	s_and_saveexec_b64 s[40:41], s[70:71]
	s_cbranch_execz .LBB0_580
.LBB0_582:
	v_add_u32_e32 v56, s93, v113
	v_add3_u32 v57, s47, v170, -1
	v_cndmask_b32_e64 v56, v57, v56, s[2:3]
	v_add_u32_e32 v56, s91, v56
	v_ashrrev_i32_e32 v57, 31, v56
	v_lshlrev_b64 v[56:57], 6, v[56:57]
	v_lshl_add_u64 v[56:57], s[72:73], 0, v[56:57]
	global_store_dword v[56:57], v123, off sc0 sc1
	s_or_b64 exec, exec, s[40:41]
	s_cmp_ge_u32 s94, s44
	s_cbranch_scc1 .LBB0_587

; __device__ __forceinline__ float bf_lo(unsigned u) { return __uint_as_float(u << 16); }
; __device__ __forceinline__ float bf_hi(unsigned u) { return __uint_as_float(u & 0xffff0000u); }
; #define MFMA16(a, b, c) __builtin_amdgcn_mfma_f32_16x16x32_bf16(a, b, c, 0, 0, 0)
; __device__ __forceinline__ void scan_phase(PREF p, char* smem, const int wid_u) {
;     ...
;       lds_barrier();
;       {
;         const int tt = wave & 1, rt = wave >> 1;
;         const f32x4 zero = {0.f, 0.f, 0.f, 0.f};
;         const bf16x8 tf = ldfrag(TT, 40, tt * 16, 0, fr, fq);
;         const f32x4 zacc = MFMA16(tf, ldfrag(VNb, 40, rt * 16, 0, fr, fq), zero);
;         const f32x4 wacc = MFMA16(tf, ldfrag(AtTb, 40, rt * 16, 0, fr, fq), zero);
;         *(uint2*)(Zb + (rt * 16 + fr) * 40 + tt * 16 + fq * 4) = pack4(zacc);
;         *(uint2*)(Wb + (rt * 16 + fr) * 40 + tt * 16 + fq * 4) = pack4(wacc);
;       }
;       lds_barrier();
;       f32x4 yacc = {0.f, 0.f, 0.f, 0.f};
;       {
;         const float pl0 = PLs[nt0 * 16 + fr], pl1 = PLs[nt1 * 16 + fr];
;         Sa = Sa * pl0; Sb = Sb * pl1;
;         const bf16x8 zf = ldfrag(Zb, 40, mt * 16, 0, fr, fq), vf = ldfrag(VT, 40, mt * 16, 0, fr, fq), wf = ldfrag(Wb, 40, mt * 16, 0, fr, fq);
;         const bf16x8 bb0 = ldfrag(Bb, 40, nt0 * 16, 0, fr, fq), bb1 = ldfrag(Bb, 40, nt1 * 16, 0, fr, fq);
;         const bf16x8 kb0 = ldfrag(Kb, 40, nt0 * 16, 0, fr, fq), kb1 = ldfrag(Kb, 40, nt1 * 16, 0, fr, fq);
;         const bf16x8 nbr = ldfrag(NbrT, 40, hn * 16, 0, fr, fq), nkr = ldfrag(NkrT, 40, hn * 16, 0, fr, fq);
;         Sa = MFMA16(zf, bb0, Sa); Sa = MFMA16(vf, kb0, Sa);
;         Sb = MFMA16(zf, bb1, Sb); Sb = MFMA16(vf, kb1, Sb);
;         yacc = MFMA16(zf, nbr, yacc); yacc = MFMA16(vf, nkr, yacc);
;         const f32x4 zero = {0.f, 0.f, 0.f, 0.f};
;         const f32x4 g0 = MFMA16(wf, bb0, zero), g1 = MFMA16(wf, bb1, zero);
;         f32x4 ry = MFMA16(wf, nbr, zero);
;         *(uint2*)(GT + (nt0 * 16 + fr) * 72 + mt * 16 + fq * 4) = pack4(g0);
;         *(uint2*)(GT + (nt1 * 16 + fr) * 72 + mt * 16 + fq * 4) = pack4(g1);
;         const uint2 rr = *(const uint2*)(Rt + (hn * 16 + fr) * 72 + mt * 16 + fq * 4);
;         ry[0] += bf_lo(rr.x); ry[1] += bf_hi(rr.x); ry[2] += bf_lo(rr.y); ry[3] += bf_hi(rr.y);
;         *(uint2*)(RyT + (hn * 16 + fr) * 72 + mt * 16 + fq * 4) = pack4(ry);
;       }
;       lds_barrier();
.Lprio_base_skip:
	s_waitcnt lgkmcnt(0)
	s_barrier
	ds_read_b128 v[56:59], v145 offset:13312
	ds_read_b128 v[60:63], v147 offset:39936
	ds_read_b128 v[64:67], v148
	s_and_b32 s40, s95, 64
	s_waitcnt lgkmcnt(1)
	v_mfma_f32_16x16x32_bf16 v[60:63], v[56:59], v[60:63], 0
	s_mulk_i32 s40, 0x90
	s_add_i32 s95, s95, 64
	s_andn2_b64 vcc, exec, s[80:81]
	s_waitcnt lgkmcnt(0)
	v_mfma_f32_16x16x32_bf16 v[56:59], v[56:59], v[64:67], 0
	s_nop 2
	v_cvt_pk_bf16_f32 v60, v60, v61
	v_cvt_pk_bf16_f32 v61, v62, v63
	s_nop 2
	v_cvt_pk_bf16_f32 v56, v56, v57
	v_cvt_pk_bf16_f32 v57, v58, v59
	ds_write2st64_b64 v149, v[56:57], v[60:61] offset0:31 offset1:41
	s_waitcnt lgkmcnt(0)
	s_barrier
	ds_read_b128 v[56:59], v147 offset:20992
	ds_read_b32 v78, v150
	ds_read_b128 v[60:63], v153
	ds_read_b128 v[64:67], v154
	ds_read_b32 v96, v151
	ds_read_b128 v[68:71], v152
	ds_read_b128 v[92:95], v147 offset:15872
	s_waitcnt lgkmcnt(5)
	v_pk_mul_f32 v[50:51], v[50:51], v[78:79] op_sel_hi:[1,0]
	v_pk_mul_f32 v[48:49], v[48:49], v[78:79] op_sel_hi:[1,0]
	s_waitcnt lgkmcnt(2)
	v_pk_mul_f32 v[54:55], v[54:55], v[96:97] op_sel_hi:[1,0]
	v_pk_mul_f32 v[52:53], v[52:53], v[96:97] op_sel_hi:[1,0]
	v_mfma_f32_16x16x32_bf16 v[48:51], v[56:59], v[60:63], v[48:51]
	ds_read_b128 v[96:99], v155
	ds_read_b128 v[100:103], v156
	v_add_u32_e32 v78, s40, v162
	s_and_b32 s40, s95, 64
	s_waitcnt lgkmcnt(2)
	v_mfma_f32_16x16x32_bf16 v[60:63], v[92:95], v[60:63], 0
	s_mulk_i32 s40, 0x90
	v_mfma_f32_16x16x32_bf16 v[52:55], v[56:59], v[64:67], v[52:55]
	v_mfma_f32_16x16x32_bf16 v[64:67], v[92:95], v[64:67], 0
	s_nop 4
	v_cvt_pk_bf16_f32 v60, v60, v61
	v_cvt_pk_bf16_f32 v61, v62, v63
	s_waitcnt lgkmcnt(1)
	v_mfma_f32_16x16x32_bf16 v[48:51], v[68:71], v[96:99], v[48:51]
	s_waitcnt lgkmcnt(0)
	v_mfma_f32_16x16x32_bf16 v[52:55], v[68:71], v[100:103], v[52:55]
	ds_read_b128 v[96:99], v145 offset:8192
	ds_read_b128 v[100:103], v145 offset:10752
	ds_write_b64 v158, v[60:61] offset:26112
	v_cvt_pk_bf16_f32 v60, v64, v65
	v_cvt_pk_bf16_f32 v61, v66, v67
	ds_write_b64 v160, v[60:61] offset:26112
	ds_read_b64 v[64:65], v161 offset:53760
	s_waitcnt lgkmcnt(4)
	v_mfma_f32_16x16x32_bf16 v[60:63], v[92:95], v[96:99], 0
	v_add_u32_e32 v92, v130, v157
	s_waitcnt lgkmcnt(0)
	v_lshlrev_b32_e32 v66, 16, v64
	v_and_b32_e32 v67, 0xffff0000, v64
	v_lshlrev_b32_e32 v64, 16, v65
	v_and_b32_e32 v65, 0xffff0000, v65
	s_nop 1
	v_pk_add_f32 v[60:61], v[60:61], v[66:67]
	v_pk_add_f32 v[62:63], v[62:63], v[64:65]
	v_cvt_pk_bf16_f32 v60, v60, v61
	v_cvt_pk_bf16_f32 v61, v62, v63
	ds_write_b64 v161, v[60:61] offset:35328
	s_waitcnt lgkmcnt(0)
	s_barrier
	s_cmp_lg_u32 s90, 1
	s_cbranch_scc1 .Lpub_skip
	s_cmp_gt_u32 s94, s44
	s_cbranch_scc1 .Lpub_skip
	s_sub_i32 s99, s94, 3
	s_max_i32 s99, s99, 0
	v_mov_b32_e32 v60, s99
	v_mov_b32_e32 v61, 0
	global_store_dword v61, v60, s[100:101] sc0 sc1
.Lpub_skip:
	ds_read_b128 v[60:63], v78
	v_mfma_f32_16x16x32_bf16 v[56:59], v[56:59], v[96:99], 0
	v_mfma_f32_16x16x32_bf16 v[56:59], v[68:71], v[100:103], v[56:59]
	ds_read_b128 v[64:67], v92 offset:26112
	ds_read_b128 v[68:71], v78 offset:64
	ds_read_b128 v[92:95], v92 offset:26176
	v_add_u32_e32 v78, v130, v159
	ds_read_b128 v[96:99], v78 offset:26176
	s_waitcnt lgkmcnt(3)
	v_mfma_f32_16x16x32_bf16 v[48:51], v[60:63], v[64:67], v[48:51]
	ds_read_b128 v[64:67], v78 offset:26112
	v_add_u32_e32 v100, v130, v128
	s_waitcnt lgkmcnt(0)
	v_mfma_f32_16x16x32_bf16 v[52:55], v[60:63], v[64:67], v[52:55]
	ds_read_b128 v[64:67], v100 offset:35328
	ds_read_b128 v[100:103], v100 offset:35392
	v_mfma_f32_16x16x32_bf16 v[48:51], v[68:71], v[92:95], v[48:51]
	v_mfma_f32_16x16x32_bf16 v[52:55], v[68:71], v[96:99], v[52:55]
	s_waitcnt lgkmcnt(1)
	v_mfma_f32_16x16x32_bf16 v[56:59], v[60:63], v[64:67], v[56:59]
	s_nop 4
	v_cvt_pk_bf16_f32 v60, v48, s0
	v_add_u32_e32 v61, s40, v168
	ds_write_b16 v61, v60
	v_cvt_pk_bf16_f32 v60, v52, s0
	ds_write_b16 v61, v60 offset:32
	v_cvt_pk_bf16_f32 v60, v49, s0
	ds_write_b16 v61, v60 offset:144
	v_cvt_pk_bf16_f32 v60, v53, s0
	s_waitcnt lgkmcnt(3)
	v_mfma_f32_16x16x32_bf16 v[56:59], v[68:71], v[100:103], v[56:59]
	ds_write_b16 v61, v60 offset:176
	v_cvt_pk_bf16_f32 v60, v50, s0
	ds_write_b16 v61, v60 offset:288
	v_cvt_pk_bf16_f32 v60, v54, s0
	ds_write_b16 v61, v60 offset:320
	v_cvt_pk_bf16_f32 v60, v51, s0
	ds_write_b16 v61, v60 offset:432
	v_cvt_pk_bf16_f32 v60, v55, s0
	ds_write_b16 v61, v60 offset:464
	s_cbranch_vccnz .LBB0_539
	ds_read_b32 v64, v81 offset:3840
	s_andn2_b64 vcc, exec, s[62:63]
	v_mov_b32_e32 v60, 1.0
	s_cbranch_vccnz .LBB0_590
	ds_read_b32 v60, v163
	s_waitcnt lgkmcnt(1)
	v_cndmask_b32_e64 v61, 1.0, v64, s[20:21]
	s_waitcnt lgkmcnt(0)
	v_mul_f32_e32 v60, v61, v60

; __device__ __forceinline__ void scan_phase(PREF p, char* smem, const int wid_u) {
;     ...
;     {
;       const int ip = (nch - 1) * 32 + hn * 16 + fr, tp = d ? T - 1 - ip : ip;
;       *(uint2*)(yout + (size_t)(r0seq + tp) * 512 + h * 64 + mt * 16 + fq * 4) = y_def;
;     }
.LBB0_603:
	s_setprio 0
	s_add_i32 s4, s92, s84
	s_sub_i32 s4, s4, 32
	s_waitcnt vmcnt(1)
	v_or_b32_e32 v0, s4, v77
	v_xad_u32 v1, v0, -1, s92
	v_cndmask_b32_e64 v0, v1, v0, s[2:3]
	v_add_u32_e32 v0, s91, v0
	v_ashrrev_i32_e32 v1, 31, v0
	v_lshlrev_b64 v[0:1], 10, v[0:1]
	v_lshl_add_u64 v[0:1], s[64:65], 0, v[0:1]
	s_lshl_b32 s2, s89, 1
	s_mov_b32 s3, 0
	v_lshl_add_u64 v[0:1], v[0:1], 0, s[2:3]
	v_lshl_add_u64 v[0:1], s[68:69], 1, v[0:1]
	v_lshlrev_b32_e32 v2, 1, v80
	v_mov_b32_e32 v3, 0
	v_lshl_add_u64 v[0:1], v[0:1], 0, v[2:3]
	global_store_dwordx2 v[0:1], v[92:93], off sc0 sc1
	s_waitcnt vmcnt(0)
	s_barrier
	s_cmp_lg_u32 s90, 1
	s_cbranch_scc1 .Lpub_fin_skip
	v_mov_b32_e32 v252, 0x1000
	v_mov_b32_e32 v253, 0
	global_store_dword v253, v252, s[100:101] sc0 sc1
.Lpub_fin_skip:
	s_load_dword s85, s[0:1], 0x120
	v_readlane_b32 s60, v254, 5
	v_readlane_b32 s54, v254, 0
	v_readlane_b32 s84, v254, 4
	v_readlane_b32 s57, v254, 2
	v_readlane_b32 s58, v254, 3
	v_readlane_b32 s61, v254, 6
	v_readlane_b32 s55, v254, 1

; #define LAS __attribute__((address_space(3)))
; #define PREF const __attribute__((address_space(4))) Params&
; #define opaque_tid() opaque_tid_w(wid_u)
; __device__ __forceinline__ unsigned xb_add(unsigned* p, unsigned v) { return __hip_atomic_fetch_add(p, v, __ATOMIC_RELAXED, __HIP_MEMORY_SCOPE_AGENT); }
; __device__ __forceinline__ unsigned xb_xcc_id() { return (unsigned)__builtin_amdgcn_s_getreg((3 << 11) | 20) & 0xFu; }
; __device__ __forceinline__ void xcd_barrier(PREF p, volatile LAS unsigned* st_, const int wid_u) {
;   asm volatile("s_waitcnt vmcnt(0)" ::: "memory");
;   __syncthreads();
;   if (opaque_tid() == 0) {
;     XcdBarrier b; b.bar = (unsigned*)(p.ws + OFF_BAR); b.x = xb_xcc_id(); b.st = st_;
;     unsigned* bar = b.bar;
;     __builtin_amdgcn_s_waitcnt(0);
;     unsigned nloc = b.st[0], nx = b.st[1];
;     if (nloc == 0u) { xcd_barrier_complete(bar, b.x, nloc, nx); b.st[0] = nloc; b.st[1] = nx; }
;     const unsigned old = xb_add(&bar[XB_XSUB(b.x)], 1u);
.LBB0_751:
	s_waitcnt vmcnt(0)
	s_waitcnt lgkmcnt(0)
	s_barrier
	v_mbcnt_lo_u32_b32 v0, -1, 0
	v_mbcnt_hi_u32_b32 v0, -1, v0
	s_nop 0
	v_cmp_eq_u32_e32 vcc, s58, v0
	s_mov_b64 s[2:3], exec
	s_branch .LBB0_824
	s_add_i32 s5, 0, 0x27a00
	v_mov_b32_e32 v0, s5
	s_getreg_b32 s4, hwreg(HW_REG_XCC_ID, 0, 4)
	s_waitcnt vmcnt(0) expcnt(0) lgkmcnt(0)
	ds_read_b32 v2, v0
	s_add_i32 s5, 0, 0x27a04
	v_mov_b32_e32 v0, s5
	ds_read_b32 v0, v0
	s_and_b32 s44, s4, 15
	s_waitcnt lgkmcnt(1)
	v_cmp_ne_u32_e32 vcc, 0, v2
	s_cbranch_vccnz .LBB0_767
	s_add_u32 s4, s48, 0x3ee90200
	s_addc_u32 s5, s49, 0
	s_add_u32 s6, s48, 0x3ee90400
	s_addc_u32 s7, s49, 0
	s_add_u32 s8, s48, 0x3ee90500
	s_addc_u32 s9, s49, 0
	s_add_u32 s10, s48, 0x3ee90600
	s_addc_u32 s11, s49, 0
	s_add_u32 s12, s48, 0x3ee90700
	s_addc_u32 s13, s49, 0
	s_add_u32 s14, s48, 0x3ee90800
	s_addc_u32 s15, s49, 0
	s_add_u32 s16, s48, 0x3ee90900
	s_addc_u32 s17, s49, 0
	s_add_u32 s18, s48, 0x3ee90a00
	s_addc_u32 s19, s49, 0
	s_add_u32 s20, s48, 0x3ee90b00
	s_addc_u32 s21, s49, 0
	s_add_u32 s22, s48, 0x3ee90c00
	s_addc_u32 s23, s49, 0
	s_add_u32 s24, s48, 0x3ee90d00
	s_addc_u32 s25, s49, 0
	s_add_u32 s26, s48, 0x3ee90e00
	s_addc_u32 s27, s49, 0
	s_add_u32 s28, s48, 0x3ee90f00
	s_addc_u32 s29, s49, 0
	s_add_u32 s30, s48, 0x3ee91000
	s_addc_u32 s31, s49, 0
	s_add_u32 s34, s48, 0x3ee91100
	s_addc_u32 s35, s49, 0
	s_add_u32 s36, s48, 0x3ee91200
	s_addc_u32 s37, s49, 0
	s_mul_i32 s45, s43, s85
	s_add_u32 s38, s48, 0x3ee91300
	s_mul_i32 s45, s45, s42
	s_addc_u32 s39, s49, 0
	s_mov_b32 s46, 1
	v_mov_b32_e32 v16, 0
	s_branch .LBB0_755

; #define opaque_tid() opaque_tid_w(wid_u)
; __device__ __forceinline__ void post_phase(PREF p, char* smem, const int wid_u, const int tile_first, const int tile_end, const int tile_step) {
;     ...
;   const int tid = opaque_tid(), w = tid >> 6, lane = tid & 63, fr = lane & 15, fq = lane >> 4;
;   bf16x8 Bg[4][6];
; #pragma unroll
;   for (int nt = 0; nt < 4; ++nt)
; #pragma unroll
;     for (int ks = 0; ks < 6; ++ks) {
;       float o[8];
; #pragma unroll
;       for (int q = 0; q < 8; ++q) { const int k = ks * 32 + fq * 8 + q; o[q] = k < 160 ? p.g2[(size_t)k * 512 + w * 64 + nt * 16 + fr] : 0.f; }
;       uint4 u = pack8(o);
;       Bg[nt][ks] = *reinterpret_cast<bf16x8*>(&u);
;     }
;   float lng[4], lnb[4];
; #pragma unroll
;   for (int nt = 0; nt < 4; ++nt) { lng[nt] = p.lnx_g[w * 64 + nt * 16 + fr]; lnb[nt] = p.lnx_b[w * 64 + nt * 16 + fr]; }
;   for (int tile = tile_first; tile < tile_end; tile += tile_step) {
.LBB0_824:
	s_or_b64 exec, exec, s[2:3]
	s_mov_b64 s[2:3], s[0:1]
	s_waitcnt lgkmcnt(0)
	s_barrier
	s_load_dwordx2 s[100:101], s[0:1], 0x110
	s_waitcnt lgkmcnt(0)
	s_add_u32 s100, s100, 0x3ee90000
	s_addc_u32 s101, s101, 0
	s_load_dwordx2 s[8:9], s[2:3], 0x110
	s_cmpk_gt_i32 s33, 0x7ff
	v_mbcnt_lo_u32_b32 v87, -1, 0
	v_mbcnt_hi_u32_b32 v87, -1, v87
	s_cbranch_scc1 .LBB0_846
	s_load_dwordx2 s[10:11], s[2:3], 0x70
	s_load_dwordx2 s[4:5], s[2:3], 0xa8
	v_add_u32_e32 v127, s84, v87
	v_and_b32_e32 v80, 0xffffffc0, v127
	v_and_b32_e32 v86, 15, v87
	v_ashrrev_i32_e32 v81, 31, v80
	s_waitcnt lgkmcnt(0)
	v_lshl_add_u64 v[0:1], v[80:81], 2, s[4:5]
	v_lshlrev_b32_e32 v120, 2, v86
	v_mov_b32_e32 v121, 0
	v_lshl_add_u64 v[0:1], v[0:1], 0, v[120:121]
	s_mov_b64 s[4:5], 0x80
	v_lshl_add_u64 v[82:83], v[0:1], 0, s[4:5]
	s_load_dwordx4 s[4:7], s[2:3], 0xc8
	v_or_b32_e32 v4, v80, v86
	v_ashrrev_i32_e32 v5, 31, v4
	v_lshlrev_b64 v[4:5], 2, v[4:5]
	v_bfe_u32 v88, v87, 4, 2
	s_mov_b64 s[12:13], 0xc0
	s_waitcnt lgkmcnt(0)
	v_lshl_add_u64 v[6:7], s[4:5], 0, v[4:5]
	v_lshl_add_u64 v[4:5], s[6:7], 0, v[4:5]
	v_lshlrev_b32_e32 v78, 14, v88
	v_lshl_add_u64 v[84:85], v[0:1], 0, s[12:13]
	global_load_dword v129, v[6:7], off
	global_load_dword v142, v[6:7], off offset:64
	global_load_dword v143, v[6:7], off offset:128
	global_load_dword v144, v[6:7], off offset:192
	global_load_dword v145, v[4:5], off
	global_load_dword v146, v[4:5], off offset:64
	global_load_dword v147, v[4:5], off offset:128
	global_load_dword v148, v[4:5], off offset:192
	v_or_b32_e32 v120, 0x40000, v78
	v_or_b32_e32 v4, 0x40800, v78
	v_mov_b32_e32 v5, v121
	v_or_b32_e32 v6, 0x41000, v78
	v_mov_b32_e32 v7, v121
	s_waitcnt vmcnt(9)
	v_or_b32_e32 v8, 0x41800, v78
	v_mov_b32_e32 v9, v121
	v_or_b32_e32 v10, 0x42000, v78
	v_mov_b32_e32 v11, v121
	v_or_b32_e32 v14, 0x42800, v78
	v_mov_b32_e32 v15, v121
	v_or_b32_e32 v12, 0x43000, v78
	v_mov_b32_e32 v13, v121
	v_lshl_add_u64 v[18:19], v[84:85], 0, v[120:121]
	v_lshl_add_u64 v[20:21], v[84:85], 0, v[4:5]
	v_lshl_add_u64 v[22:23], v[84:85], 0, v[6:7]
	v_lshl_add_u64 v[24:25], v[84:85], 0, v[8:9]
	v_lshl_add_u64 v[26:27], v[84:85], 0, v[10:11]
	v_lshl_add_u64 v[28:29], v[84:85], 0, v[14:15]
	v_lshl_add_u64 v[30:31], v[84:85], 0, v[12:13]
	v_or_b32_e32 v16, 0x43800, v78
	v_mov_b32_e32 v17, v121
	v_lshl_add_u64 v[32:33], v[84:85], 0, v[16:17]
	global_load_dword v89, v[18:19], off
	global_load_dword v90, v[20:21], off
	global_load_dword v91, v[22:23], off
	global_load_dword v92, v[24:25], off
	global_load_dword v93, v[26:27], off
	global_load_dword v94, v[28:29], off
	global_load_dword v95, v[30:31], off
	global_load_dword v96, v[32:33], off
	v_or_b32_e32 v18, 0x30000, v78
	v_mov_b32_e32 v19, v121
	v_or_b32_e32 v20, 0x30800, v78
	v_mov_b32_e32 v21, v121
	v_or_b32_e32 v22, 0x31000, v78
	v_mov_b32_e32 v23, v121
	v_or_b32_e32 v24, 0x31800, v78
	v_mov_b32_e32 v25, v121
	v_or_b32_e32 v26, 0x32000, v78
	v_mov_b32_e32 v27, v121
	v_or_b32_e32 v30, 0x32800, v78
	v_mov_b32_e32 v31, v121
	v_or_b32_e32 v28, 0x33000, v78
	v_mov_b32_e32 v29, v121
	v_lshl_add_u64 v[34:35], v[84:85], 0, v[18:19]
	v_lshl_add_u64 v[36:37], v[84:85], 0, v[20:21]
	v_lshl_add_u64 v[38:39], v[84:85], 0, v[22:23]
	v_lshl_add_u64 v[40:41], v[84:85], 0, v[24:25]
	v_lshl_add_u64 v[42:43], v[84:85], 0, v[26:27]
	v_lshl_add_u64 v[44:45], v[84:85], 0, v[30:31]
	v_lshl_add_u64 v[46:47], v[84:85], 0, v[28:29]
	v_or_b32_e32 v32, 0x33800, v78
	v_mov_b32_e32 v33, v121
	v_lshl_add_u64 v[48:49], v[84:85], 0, v[32:33]
	global_load_dword v97, v[34:35], off
	global_load_dword v98, v[36:37], off
	global_load_dword v99, v[38:39], off
	global_load_dword v100, v[40:41], off
	global_load_dword v101, v[42:43], off
	global_load_dword v102, v[44:45], off
	global_load_dword v103, v[46:47], off
	global_load_dword v104, v[48:49], off
	v_or_b32_e32 v34, 0x20000, v78
	v_mov_b32_e32 v35, v121
	v_or_b32_e32 v36, 0x20800, v78
	v_mov_b32_e32 v37, v121
	v_or_b32_e32 v38, 0x21000, v78
	v_mov_b32_e32 v39, v121
	v_or_b32_e32 v40, 0x21800, v78
	v_mov_b32_e32 v41, v121
	v_or_b32_e32 v42, 0x22000, v78
	v_mov_b32_e32 v43, v121
	v_or_b32_e32 v46, 0x22800, v78
	v_mov_b32_e32 v47, v121
	v_or_b32_e32 v44, 0x23000, v78
	v_mov_b32_e32 v45, v121
	v_lshl_add_u64 v[50:51], v[84:85], 0, v[34:35]
	v_lshl_add_u64 v[52:53], v[84:85], 0, v[36:37]
	v_lshl_add_u64 v[54:55], v[84:85], 0, v[38:39]
	v_lshl_add_u64 v[56:57], v[84:85], 0, v[40:41]
	v_lshl_add_u64 v[58:59], v[84:85], 0, v[42:43]
	v_lshl_add_u64 v[60:61], v[84:85], 0, v[46:47]
	v_lshl_add_u64 v[62:63], v[84:85], 0, v[44:45]
	v_or_b32_e32 v48, 0x23800, v78
	v_mov_b32_e32 v49, v121
	v_lshl_add_u64 v[64:65], v[84:85], 0, v[48:49]
	global_load_dword v105, v[50:51], off
	global_load_dword v106, v[52:53], off
	global_load_dword v107, v[54:55], off
	global_load_dword v108, v[56:57], off
	global_load_dword v109, v[58:59], off
	global_load_dword v110, v[60:61], off
	global_load_dword v111, v[62:63], off
	global_load_dword v112, v[64:65], off
	v_or_b32_e32 v50, 0x10000, v78
	v_mov_b32_e32 v51, v121
	v_or_b32_e32 v52, 0x10800, v78
	v_mov_b32_e32 v53, v121
	v_or_b32_e32 v54, 0x11000, v78
	v_mov_b32_e32 v55, v121
	v_or_b32_e32 v56, 0x11800, v78
	v_mov_b32_e32 v57, v121
	v_or_b32_e32 v58, 0x12000, v78
	v_mov_b32_e32 v59, v121
	v_or_b32_e32 v62, 0x12800, v78
	v_mov_b32_e32 v63, v121
	v_or_b32_e32 v60, 0x13000, v78
	v_mov_b32_e32 v61, v121
	v_lshl_add_u64 v[66:67], v[84:85], 0, v[50:51]
	v_lshl_add_u64 v[68:69], v[84:85], 0, v[52:53]
	v_lshl_add_u64 v[70:71], v[84:85], 0, v[54:55]
	v_lshl_add_u64 v[72:73], v[84:85], 0, v[56:57]
	v_lshl_add_u64 v[74:75], v[84:85], 0, v[58:59]
	v_lshl_add_u64 v[76:77], v[84:85], 0, v[62:63]
; __device__ __forceinline__ void post_phase(PREF p, char* smem, const int wid_u, const int tile_first, const int tile_end, const int tile_step) {
;     ...
; #pragma unroll
;   for (int nt = 0; nt < 4; ++nt)
; #pragma unroll
;     for (int ks = 0; ks < 6; ++ks) {
;       float o[8];
; #pragma unroll
;       for (int q = 0; q < 8; ++q) { const int k = ks * 32 + fq * 8 + q; o[q] = k < 160 ? p.g2[(size_t)k * 512 + w * 64 + nt * 16 + fr] : 0.f; }
;       uint4 u = pack8(o);
;       Bg[nt][ks] = *reinterpret_cast<bf16x8*>(&u);
;     }
	v_lshl_add_u64 v[122:123], v[84:85], 0, v[60:61]
	v_or_b32_e32 v64, 0x13800, v78
	v_mov_b32_e32 v65, v121
	v_mov_b32_e32 v79, v121
	v_lshl_add_u64 v[124:125], v[84:85], 0, v[64:65]
	global_load_dword v113, v[66:67], off
	global_load_dword v114, v[68:69], off
	global_load_dword v115, v[70:71], off
	global_load_dword v116, v[72:73], off
	global_load_dword v117, v[74:75], off
	global_load_dword v118, v[76:77], off
	global_load_dword v119, v[122:123], off
	s_nop 0
	global_load_dword v122, v[124:125], off
	v_lshl_add_u64 v[66:67], v[0:1], 0, v[78:79]
	v_or_b32_e32 v68, 0x1000, v78
	v_mov_b32_e32 v69, v121
	v_or_b32_e32 v70, 0x1800, v78
	v_mov_b32_e32 v71, v121
	v_or_b32_e32 v72, 0x2000, v78
	v_mov_b32_e32 v73, v121
	v_or_b32_e32 v74, 0x2800, v78
	v_mov_b32_e32 v75, v121
	v_or_b32_e32 v76, 0x3000, v78
	v_mov_b32_e32 v77, v121
	v_or_b32_e32 v78, 0x3800, v78
	v_lshl_add_u64 v[124:125], v[84:85], 0, v[68:69]
	v_lshl_add_u64 v[130:131], v[84:85], 0, v[70:71]
	v_lshl_add_u64 v[132:133], v[84:85], 0, v[72:73]
	v_lshl_add_u64 v[134:135], v[84:85], 0, v[74:75]
	v_lshl_add_u64 v[136:137], v[84:85], 0, v[76:77]
	v_lshl_add_u64 v[138:139], v[84:85], 0, v[78:79]
	v_lshl_add_u64 v[140:141], v[82:83], 0, v[120:121]
	v_lshl_add_u64 v[150:151], v[82:83], 0, v[4:5]
	global_load_dword v84, v[124:125], off
	global_load_dword v85, v[130:131], off
	global_load_dword v123, v[132:133], off
	s_nop 0
	global_load_dword v124, v[134:135], off
	global_load_dword v125, v[136:137], off
	global_load_dword v126, v[138:139], off
	global_load_dword v128, v[140:141], off
	global_load_dword v130, v[150:151], off
	v_lshl_add_u64 v[132:133], v[82:83], 0, v[6:7]
	v_lshl_add_u64 v[134:135], v[82:83], 0, v[8:9]
	v_lshl_add_u64 v[136:137], v[82:83], 0, v[10:11]
	v_lshl_add_u64 v[138:139], v[82:83], 0, v[14:15]
	v_lshl_add_u64 v[154:155], v[82:83], 0, v[20:21]
	v_lshl_add_u64 v[140:141], v[82:83], 0, v[12:13]
	v_lshl_add_u64 v[150:151], v[82:83], 0, v[16:17]
	v_lshl_add_u64 v[152:153], v[82:83], 0, v[18:19]
	global_load_dword v131, v[132:133], off
	global_load_dword v149, v[134:135], off
	global_load_dword v156, v[136:137], off
	global_load_dword v157, v[138:139], off
	global_load_dword v158, v[140:141], off
	global_load_dword v159, v[150:151], off
	global_load_dword v160, v[152:153], off
	global_load_dword v161, v[154:155], off
	v_lshl_add_u64 v[132:133], v[82:83], 0, v[22:23]
	v_lshl_add_u64 v[134:135], v[82:83], 0, v[24:25]
	v_lshl_add_u64 v[136:137], v[82:83], 0, v[26:27]
	v_lshl_add_u64 v[138:139], v[82:83], 0, v[30:31]
	v_lshl_add_u64 v[154:155], v[82:83], 0, v[36:37]
	v_lshl_add_u64 v[140:141], v[82:83], 0, v[28:29]
	v_lshl_add_u64 v[150:151], v[82:83], 0, v[32:33]
	v_lshl_add_u64 v[152:153], v[82:83], 0, v[34:35]
	global_load_dword v162, v[132:133], off
	global_load_dword v163, v[134:135], off
	global_load_dword v164, v[136:137], off
	global_load_dword v165, v[138:139], off
	global_load_dword v166, v[140:141], off
	global_load_dword v167, v[150:151], off
	global_load_dword v168, v[152:153], off
	global_load_dword v169, v[154:155], off
	v_lshl_add_u64 v[132:133], v[82:83], 0, v[38:39]
	v_lshl_add_u64 v[134:135], v[82:83], 0, v[40:41]
	v_lshl_add_u64 v[136:137], v[82:83], 0, v[42:43]
	v_lshl_add_u64 v[138:139], v[82:83], 0, v[46:47]
	v_lshl_add_u64 v[154:155], v[82:83], 0, v[52:53]
	v_lshl_add_u64 v[2:3], v[0:1], 0, 64
	v_lshl_add_u64 v[140:141], v[82:83], 0, v[44:45]
	v_lshl_add_u64 v[150:151], v[82:83], 0, v[48:49]
	v_lshl_add_u64 v[152:153], v[82:83], 0, v[50:51]
	global_load_dword v170, v[132:133], off
	global_load_dword v171, v[134:135], off
	global_load_dword v172, v[136:137], off
	global_load_dword v173, v[138:139], off
	global_load_dword v174, v[140:141], off
	global_load_dword v175, v[150:151], off
	global_load_dword v176, v[152:153], off
	global_load_dword v177, v[154:155], off
	v_lshl_add_u64 v[132:133], v[82:83], 0, v[54:55]
	v_lshl_add_u64 v[134:135], v[82:83], 0, v[56:57]
	v_lshl_add_u64 v[136:137], v[82:83], 0, v[58:59]
	v_lshl_add_u64 v[138:139], v[82:83], 0, v[62:63]
	v_lshl_add_u64 v[154:155], v[82:83], 0, v[70:71]
	v_lshl_add_u64 v[140:141], v[82:83], 0, v[60:61]
	v_lshl_add_u64 v[150:151], v[82:83], 0, v[64:65]
	v_lshl_add_u64 v[152:153], v[82:83], 0, v[68:69]
	global_load_dword v178, v[132:133], off
	global_load_dword v179, v[134:135], off
	global_load_dword v180, v[136:137], off
	global_load_dword v181, v[138:139], off
	global_load_dword v182, v[140:141], off
	global_load_dword v183, v[150:151], off
	global_load_dword v184, v[152:153], off
	s_nop 0
	global_load_dword v154, v[154:155], off
	v_lshl_add_u64 v[132:133], v[82:83], 0, v[72:73]
	v_lshl_add_u64 v[134:135], v[82:83], 0, v[74:75]
	v_lshl_add_u64 v[136:137], v[82:83], 0, v[76:77]
	v_lshl_add_u64 v[82:83], v[82:83], 0, v[78:79]
	v_lshl_add_u64 v[138:139], v[2:3], 0, v[120:121]
	v_lshl_add_u64 v[140:141], v[2:3], 0, v[4:5]
	v_lshl_add_u64 v[150:151], v[2:3], 0, v[6:7]
	v_lshl_add_u64 v[152:153], v[2:3], 0, v[8:9]
	global_load_dword v155, v[132:133], off
	global_load_dword v185, v[134:135], off
	global_load_dword v186, v[136:137], off
	global_load_dword v187, v[82:83], off
	global_load_dword v188, v[138:139], off
	global_load_dword v189, v[140:141], off
	global_load_dword v190, v[150:151], off
	global_load_dword v191, v[152:153], off
	v_lshl_add_u64 v[82:83], v[2:3], 0, v[10:11]
	v_lshl_add_u64 v[132:133], v[2:3], 0, v[14:15]
	v_lshl_add_u64 v[134:135], v[2:3], 0, v[12:13]
	v_lshl_add_u64 v[136:137], v[2:3], 0, v[16:17]
	v_lshl_add_u64 v[138:139], v[2:3], 0, v[18:19]
	v_lshl_add_u64 v[140:141], v[2:3], 0, v[20:21]
	v_lshl_add_u64 v[150:151], v[2:3], 0, v[22:23]
	v_lshl_add_u64 v[152:153], v[2:3], 0, v[24:25]
; __device__ __forceinline__ void post_phase(PREF p, char* smem, const int wid_u, const int tile_first, const int tile_end, const int tile_step) {
;     ...
; #pragma unroll
;   for (int nt = 0; nt < 4; ++nt)
; #pragma unroll
;     for (int ks = 0; ks < 6; ++ks) {
;       float o[8];
; #pragma unroll
;       for (int q = 0; q < 8; ++q) { const int k = ks * 32 + fq * 8 + q; o[q] = k < 160 ? p.g2[(size_t)k * 512 + w * 64 + nt * 16 + fr] : 0.f; }
;       uint4 u = pack8(o);
;       Bg[nt][ks] = *reinterpret_cast<bf16x8*>(&u);
;     }
;   float lng[4], lnb[4];
; #pragma unroll
;   for (int nt = 0; nt < 4; ++nt) { lng[nt] = p.lnx_g[w * 64 + nt * 16 + fr]; lnb[nt] = p.lnx_b[w * 64 + nt * 16 + fr]; }
	global_load_dword v192, v[82:83], off
	global_load_dword v193, v[132:133], off
	global_load_dword v194, v[134:135], off
	global_load_dword v195, v[136:137], off
	global_load_dword v196, v[138:139], off
	global_load_dword v197, v[140:141], off
	global_load_dword v198, v[150:151], off
	global_load_dword v199, v[152:153], off
	v_lshl_add_u64 v[82:83], v[2:3], 0, v[26:27]
	v_lshl_add_u64 v[132:133], v[2:3], 0, v[30:31]
	v_lshl_add_u64 v[134:135], v[2:3], 0, v[28:29]
	v_lshl_add_u64 v[136:137], v[2:3], 0, v[32:33]
	v_lshl_add_u64 v[138:139], v[2:3], 0, v[34:35]
	v_lshl_add_u64 v[140:141], v[2:3], 0, v[36:37]
	v_lshl_add_u64 v[150:151], v[2:3], 0, v[38:39]
	v_lshl_add_u64 v[152:153], v[2:3], 0, v[40:41]
	global_load_dword v200, v[82:83], off
	global_load_dword v201, v[132:133], off
	global_load_dword v202, v[134:135], off
	global_load_dword v203, v[136:137], off
	global_load_dword v204, v[138:139], off
	global_load_dword v205, v[140:141], off
	global_load_dword v206, v[150:151], off
	global_load_dword v207, v[152:153], off
	v_lshl_add_u64 v[82:83], v[2:3], 0, v[42:43]
	v_lshl_add_u64 v[132:133], v[2:3], 0, v[46:47]
	v_lshl_add_u64 v[134:135], v[2:3], 0, v[44:45]
	v_lshl_add_u64 v[136:137], v[2:3], 0, v[48:49]
	v_lshl_add_u64 v[138:139], v[2:3], 0, v[50:51]
	v_lshl_add_u64 v[140:141], v[2:3], 0, v[52:53]
	v_lshl_add_u64 v[150:151], v[2:3], 0, v[54:55]
	v_lshl_add_u64 v[152:153], v[2:3], 0, v[56:57]
	global_load_dword v208, v[82:83], off
	global_load_dword v209, v[132:133], off
	global_load_dword v210, v[134:135], off
	global_load_dword v211, v[136:137], off
	global_load_dword v212, v[138:139], off
	global_load_dword v213, v[140:141], off
	global_load_dword v214, v[150:151], off
	global_load_dword v215, v[152:153], off
	v_lshl_add_u64 v[82:83], v[2:3], 0, v[58:59]
	v_lshl_add_u64 v[132:133], v[2:3], 0, v[62:63]
	v_lshl_add_u64 v[134:135], v[2:3], 0, v[60:61]
	v_lshl_add_u64 v[136:137], v[2:3], 0, v[64:65]
	v_lshl_add_u64 v[138:139], v[2:3], 0, v[68:69]
	global_load_dword v216, v[66:67], off offset:192
	global_load_dword v217, v[66:67], off offset:2240
	global_load_dword v218, v[66:67], off offset:2176
	global_load_dword v219, v[66:67], off offset:2112
	global_load_dword v220, v[66:67], off offset:2048
	global_load_dword v221, v[66:67], off offset:128
	global_load_dword v222, v[66:67], off offset:64
	v_lshl_add_u64 v[140:141], v[2:3], 0, v[70:71]
	v_lshl_add_u64 v[150:151], v[2:3], 0, v[72:73]
	v_lshl_add_u64 v[152:153], v[2:3], 0, v[74:75]
	global_load_dword v223, v[82:83], off
	global_load_dword v224, v[132:133], off
	s_nop 0
	global_load_dword v134, v[134:135], off
	s_nop 0
	global_load_dword v135, v[136:137], off
	s_nop 0
	global_load_dword v136, v[138:139], off
	global_load_dword v137, v[140:141], off
	s_nop 0
	global_load_dword v138, v[150:151], off
	global_load_dword v139, v[152:153], off
	v_lshl_add_u64 v[82:83], v[2:3], 0, v[76:77]
	v_lshl_add_u64 v[132:133], v[0:1], 0, v[120:121]
	v_lshl_add_u64 v[2:3], v[2:3], 0, v[78:79]
	v_lshl_add_u64 v[4:5], v[0:1], 0, v[4:5]
	v_lshl_add_u64 v[6:7], v[0:1], 0, v[6:7]
	v_lshl_add_u64 v[8:9], v[0:1], 0, v[8:9]
	v_lshl_add_u64 v[10:11], v[0:1], 0, v[10:11]
	v_lshl_add_u64 v[14:15], v[0:1], 0, v[14:15]
	global_load_dword v82, v[82:83], off
	s_nop 0
	global_load_dword v83, v[2:3], off
	global_load_dword v120, v[132:133], off
	s_nop 0
	global_load_dword v132, v[4:5], off
	global_load_dword v133, v[6:7], off
	global_load_dword v140, v[8:9], off
	global_load_dword v141, v[10:11], off
	global_load_dword v150, v[14:15], off
	v_lshl_add_u64 v[2:3], v[0:1], 0, v[12:13]
	v_lshl_add_u64 v[4:5], v[0:1], 0, v[16:17]
	v_lshl_add_u64 v[6:7], v[0:1], 0, v[18:19]
	v_lshl_add_u64 v[8:9], v[0:1], 0, v[20:21]
	v_lshl_add_u64 v[10:11], v[0:1], 0, v[22:23]
	v_lshl_add_u64 v[12:13], v[0:1], 0, v[24:25]
	v_lshl_add_u64 v[14:15], v[0:1], 0, v[26:27]
	v_lshl_add_u64 v[16:17], v[0:1], 0, v[30:31]
	global_load_dword v151, v[2:3], off
	global_load_dword v152, v[4:5], off
	global_load_dword v153, v[6:7], off
	global_load_dword v225, v[8:9], off
	global_load_dword v226, v[10:11], off
	global_load_dword v227, v[12:13], off
	global_load_dword v228, v[14:15], off
	global_load_dword v229, v[16:17], off
	v_lshl_add_u64 v[2:3], v[0:1], 0, v[28:29]
	v_lshl_add_u64 v[4:5], v[0:1], 0, v[32:33]
	v_lshl_add_u64 v[6:7], v[0:1], 0, v[34:35]
	v_lshl_add_u64 v[8:9], v[0:1], 0, v[36:37]
	v_lshl_add_u64 v[10:11], v[0:1], 0, v[38:39]
	v_lshl_add_u64 v[12:13], v[0:1], 0, v[40:41]
	v_lshl_add_u64 v[14:15], v[0:1], 0, v[42:43]
	v_lshl_add_u64 v[16:17], v[0:1], 0, v[46:47]
	global_load_dword v230, v[2:3], off
	global_load_dword v231, v[4:5], off
	global_load_dword v232, v[6:7], off
	global_load_dword v233, v[8:9], off
	global_load_dword v234, v[10:11], off
	global_load_dword v235, v[12:13], off
	global_load_dword v236, v[14:15], off
	global_load_dword v237, v[16:17], off
	v_lshl_add_u64 v[2:3], v[0:1], 0, v[44:45]
	v_lshl_add_u64 v[4:5], v[0:1], 0, v[48:49]
	v_lshl_add_u64 v[6:7], v[0:1], 0, v[50:51]
	v_lshl_add_u64 v[8:9], v[0:1], 0, v[52:53]
	v_lshl_add_u64 v[10:11], v[0:1], 0, v[54:55]
	v_lshl_add_u64 v[12:13], v[0:1], 0, v[56:57]
	v_lshl_add_u64 v[14:15], v[0:1], 0, v[58:59]
	v_lshl_add_u64 v[16:17], v[0:1], 0, v[62:63]
	global_load_dword v238, v[2:3], off
	global_load_dword v239, v[4:5], off
	global_load_dword v240, v[6:7], off
	global_load_dword v241, v[8:9], off
	global_load_dword v242, v[10:11], off
	global_load_dword v243, v[12:13], off
	global_load_dword v244, v[14:15], off
	global_load_dword v245, v[16:17], off
	v_lshl_add_u64 v[2:3], v[0:1], 0, v[60:61]
	v_lshl_add_u64 v[4:5], v[0:1], 0, v[64:65]
	global_load_dword v246, v[66:67], off
	v_lshl_add_u64 v[6:7], v[0:1], 0, v[68:69]
	v_lshl_add_u64 v[8:9], v[0:1], 0, v[70:71]
	v_lshl_add_u64 v[10:11], v[0:1], 0, v[72:73]
	v_lshl_add_u64 v[12:13], v[0:1], 0, v[74:75]
	v_lshl_add_u64 v[14:15], v[0:1], 0, v[76:77]
	v_lshl_add_u64 v[0:1], v[0:1], 0, v[78:79]
	global_load_dword v75, v[2:3], off
	global_load_dword v76, v[4:5], off
	global_load_dword v77, v[6:7], off
	global_load_dword v78, v[8:9], off
	global_load_dword v79, v[10:11], off
	global_load_dword v247, v[12:13], off
	global_load_dword v248, v[14:15], off
	global_load_dword v249, v[0:1], off
	s_waitcnt vmcnt(62)
; __device__ __forceinline__ void post_phase(PREF p, char* smem, const int wid_u, const int tile_first, const int tile_end, const int tile_step) {
;     ...
;   bf16x8 Bg[4][6];
; #pragma unroll
;   for (int nt = 0; nt < 4; ++nt)
; #pragma unroll
;     for (int ks = 0; ks < 6; ++ks) {
;       float o[8];
; #pragma unroll
;       for (int q = 0; q < 8; ++q) { const int k = ks * 32 + fq * 8 + q; o[q] = k < 160 ? p.g2[(size_t)k * 512 + w * 64 + nt * 16 + fr] : 0.f; }
;       uint4 u = pack8(o);
;       Bg[nt][ks] = *reinterpret_cast<bf16x8*>(&u);
;     }
;   float lng[4], lnb[4];
; #pragma unroll
;   for (int nt = 0; nt < 4; ++nt) { lng[nt] = p.lnx_g[w * 64 + nt * 16 + fr]; lnb[nt] = p.lnx_b[w * 64 + nt * 16 + fr]; }
;   for (int tile = tile_first; tile < tile_end; tile += tile_step) {
	v_cvt_pk_bf16_f32 v0, v89, v90
	v_cvt_pk_bf16_f32 v1, v91, v92
	v_cvt_pk_bf16_f32 v17, v84, v85
	v_lshlrev_b32_e32 v84, 1, v86
	s_mov_b64 s[6:7], 0xee90000
	v_cvt_pk_bf16_f32 v15, v119, v122
	v_cvt_pk_bf16_f32 v18, v123, v124
	v_add_u32_e32 v85, 0, v84
	v_cvt_pk_bf16_f32 v19, v125, v126
	v_cvt_pk_bf16_f32 v20, v128, v130
	v_cvt_pk_bf16_f32 v21, v131, v149
	v_lshlrev_b32_e32 v149, 2, v88
	s_add_u32 s12, s8, 0x1ae90000
	v_lshl_add_u32 v89, v88, 4, 0
	s_movk_i32 s19, 0x810
	s_addc_u32 s13, s9, 0
	v_cvt_pk_bf16_f32 v22, v156, v157
	s_mov_b32 s4, 0
	s_movk_i32 s2, 0x300
	v_cvt_pk_bf16_f32 v2, v93, v94
	v_cvt_pk_bf16_f32 v3, v95, v96
	v_cvt_pk_bf16_f32 v4, v97, v98
	v_cvt_pk_bf16_f32 v5, v99, v100
	v_cvt_pk_bf16_f32 v6, v101, v102
	v_cvt_pk_bf16_f32 v7, v103, v104
	v_cvt_pk_bf16_f32 v8, v105, v106
	v_cvt_pk_bf16_f32 v9, v107, v108
	v_cvt_pk_bf16_f32 v10, v109, v110
	s_waitcnt vmcnt(45)
	v_cvt_pk_bf16_f32 v55, v134, v135
	v_cvt_pk_bf16_f32 v11, v111, v112
	v_cvt_pk_bf16_f32 v12, v113, v114
	v_cvt_pk_bf16_f32 v13, v115, v116
	v_cvt_pk_bf16_f32 v14, v117, v118
	v_cvt_pk_bf16_f32 v16, v216, v217
	v_cvt_pk_bf16_f32 v23, v158, v159
	s_waitcnt vmcnt(39)
	v_cvt_pk_bf16_f32 v59, v82, v83
	v_lshlrev_b32_e32 v83, 3, v87
	v_and_b32_e32 v87, 0x1f8, v83
	s_waitcnt vmcnt(37)
	v_cvt_pk_bf16_f32 v60, v120, v132
	v_lshlrev_b32_e32 v120, 1, v87
	v_lshl_add_u64 v[90:91], s[8:9], 0, v[120:121]
	v_ashrrev_i32_e32 v82, 6, v127
	v_lshl_add_u64 v[122:123], v[90:91], 0, s[6:7]
	s_mov_b64 s[6:7], 0x14e90000
	v_lshlrev_b32_e32 v83, 2, v80
	v_lshl_add_u64 v[124:125], v[90:91], 0, s[6:7]
	v_add3_u32 v90, v85, v84, v83
	v_ashrrev_i32_e32 v83, 31, v82
	v_lshl_add_u64 v[82:83], v[82:83], 3, s[8:9]
	s_mov_b64 s[6:7], 0x2890000
	v_lshl_add_u64 v[130:131], v[82:83], 0, s[6:7]
	v_lshl_add_u32 v82, v80, 1, v85
	v_lshl_add_u64 v[80:81], v[80:81], 1, s[8:9]
	v_mov_b32_e32 v85, v121
	v_lshl_add_u64 v[80:81], v[80:81], 0, v[84:85]
	s_mov_b64 s[6:7], 0x2e90400
	s_waitcnt vmcnt(35)
	v_cvt_pk_bf16_f32 v61, v133, v140
	v_lshl_add_u64 v[132:133], v[80:81], 0, s[6:7]
	v_lshlrev_b32_e32 v80, 2, v87
	v_mov_b32_e32 v81, v121
	v_lshl_add_u64 v[80:81], s[10:11], 0, v[80:81]
	s_mov_b64 s[6:7], 0x1000
	s_waitcnt vmcnt(33)
	v_cvt_pk_bf16_f32 v62, v141, v150
	v_lshl_add_u64 v[134:135], v[80:81], 0, s[6:7]
	v_mul_u32_u24_e32 v80, 0x190, v86
	v_or_b32_e32 v150, 1, v149
	v_mov_b32_e32 v86, 0x78f0
	v_add_u32_e32 v126, 0, v120
	v_mul_u32_u24_e32 v81, 0x2040, v88
	v_mul_u32_u24_e32 v83, 0x1040, v88
	v_mul_u32_u24_e32 v84, 0x810, v150
	v_mul_u32_u24_e32 v85, 0x410, v150
	v_mad_u32_u24 v86, v150, s19, v86
	v_add_u32_e32 v157, v89, v80
	v_mov_b32_e32 v80, 0x900
	v_cvt_pk_bf16_f32 v24, v160, v161
	v_cvt_pk_bf16_f32 v25, v162, v163
	v_cvt_pk_bf16_f32 v26, v164, v165
	v_cvt_pk_bf16_f32 v27, v166, v167
	v_cvt_pk_bf16_f32 v28, v168, v169
	v_cvt_pk_bf16_f32 v29, v170, v171
	v_cvt_pk_bf16_f32 v30, v172, v173
	v_cvt_pk_bf16_f32 v31, v174, v175
	v_cvt_pk_bf16_f32 v32, v176, v177
	v_cvt_pk_bf16_f32 v33, v178, v179
	v_cvt_pk_bf16_f32 v34, v180, v181
	v_cvt_pk_bf16_f32 v35, v182, v183
	v_cvt_pk_bf16_f32 v36, v221, v218
	v_cvt_pk_bf16_f32 v37, v184, v154
	v_cvt_pk_bf16_f32 v38, v155, v185
	v_cvt_pk_bf16_f32 v39, v186, v187
	v_cvt_pk_bf16_f32 v40, v188, v189
	v_cvt_pk_bf16_f32 v41, v190, v191
	v_cvt_pk_bf16_f32 v42, v192, v193
	v_cvt_pk_bf16_f32 v43, v194, v195
	v_cvt_pk_bf16_f32 v44, v196, v197
	v_cvt_pk_bf16_f32 v45, v198, v199
	v_cvt_pk_bf16_f32 v46, v200, v201
	v_cvt_pk_bf16_f32 v47, v202, v203
	v_cvt_pk_bf16_f32 v48, v204, v205
	v_cvt_pk_bf16_f32 v49, v206, v207
	v_cvt_pk_bf16_f32 v50, v208, v209
	v_cvt_pk_bf16_f32 v51, v210, v211
	v_cvt_pk_bf16_f32 v52, v212, v213
	v_cvt_pk_bf16_f32 v53, v214, v215
	v_cvt_pk_bf16_f32 v54, v223, v224
	v_cvt_pk_bf16_f32 v56, v222, v219
	v_cvt_pk_bf16_f32 v57, v136, v137
	v_cvt_pk_bf16_f32 v58, v138, v139
	s_waitcnt vmcnt(31)
	v_cvt_pk_bf16_f32 v63, v151, v152
	s_waitcnt vmcnt(29)
	v_cvt_pk_bf16_f32 v64, v153, v225
	s_waitcnt vmcnt(27)
	v_cvt_pk_bf16_f32 v65, v226, v227
	s_waitcnt vmcnt(25)
	v_cvt_pk_bf16_f32 v66, v228, v229
	s_waitcnt vmcnt(23)
	v_cvt_pk_bf16_f32 v67, v230, v231
	s_waitcnt vmcnt(21)
	v_cvt_pk_bf16_f32 v68, v232, v233
	s_waitcnt vmcnt(19)
	v_cvt_pk_bf16_f32 v69, v234, v235
	s_waitcnt vmcnt(17)
	v_cvt_pk_bf16_f32 v70, v236, v237
	s_waitcnt vmcnt(15)
	v_cvt_pk_bf16_f32 v71, v238, v239
	s_waitcnt vmcnt(13)
	v_cvt_pk_bf16_f32 v72, v240, v241
	s_waitcnt vmcnt(11)
	v_cvt_pk_bf16_f32 v73, v242, v243
	s_waitcnt vmcnt(9)
	v_cvt_pk_bf16_f32 v74, v244, v245
	s_waitcnt vmcnt(6)
	v_cvt_pk_bf16_f32 v75, v75, v76
	v_cvt_pk_bf16_f32 v76, v246, v220
	s_waitcnt vmcnt(4)
	v_cvt_pk_bf16_f32 v77, v77, v78
	s_waitcnt vmcnt(2)
	v_cvt_pk_bf16_f32 v78, v79, v247
	s_waitcnt vmcnt(0)
	v_cvt_pk_bf16_f32 v79, v248, v249
	v_cmp_gt_i32_e64 s[2:3], s2, v127
	v_add_u32_e32 v128, v126, v120
	s_movk_i32 s28, 0x410
	v_or_b32_e32 v151, 2, v149
	v_or_b32_e32 v152, 3, v149
	v_or_b32_e32 v153, 16, v149
	v_or_b32_e32 v154, 17, v149
	v_or_b32_e32 v155, 18, v149
	v_or_b32_e32 v156, 19, v149
	v_lshl_add_u64 v[136:137], s[12:13], 0, v[120:121]
	s_movk_i32 s29, 0xfe0
	s_movk_i32 s30, 0xfff
	s_mov_b32 s31, 0x2aaaaaab
	s_movk_i32 s34, 0xffe8
	s_movk_i32 s35, 0xff40
	s_movk_i32 s36, 0x1400
	s_movk_i32 s37, 0xff
	s_mov_b64 s[14:15], 0xc00
	s_mov_b32 s5, s4
	s_mov_b32 s6, s4
	s_mov_b32 s7, s4
	v_add_u32_e32 v158, v90, v81
	s_mov_b32 s16, 0x3c800000
	v_add_u32_e32 v159, v82, v83
	v_add_u32_e32 v160, v90, v84
	s_mov_b32 s18, 0x3a27c5ac
	s_mov_b32 s38, 0x800000
	v_add_u32_e32 v161, v82, v85
	v_add_u32_e32 v162, v90, v86
	v_lshl_add_u32 v163, v127, 3, v80
	s_branch .LBB0_827
; __device__ __forceinline__ float bf2f(bf16_t b) { return __uint_as_float(((unsigned)b) << 16); }
; __device__ __forceinline__ void post_phase(PREF p, char* smem, const int wid_u, const int tile_first, const int tile_end, const int tile_step) {
;     ...
;     f32x4 acc[2][4] = {};
; #pragma unroll
;     for (int ks = 0; ks < 6; ++ks) {
;       bf16x8 a[2];
; #pragma unroll
;       for (int mt = 0; mt < 2; ++mt) a[mt] = *reinterpret_cast<const bf16x8*>(Ag + (mt * 16 + fr) * 200 + ks * 32 + fq * 8);
; #pragma unroll
;       for (int mt = 0; mt < 2; ++mt)
; #pragma unroll
;         for (int nt = 0; nt < 4; ++nt) acc[mt][nt] = __builtin_amdgcn_mfma_f32_16x16x32_bf16(a[mt], Bg[nt][ks], acc[mt][nt], 0, 0, 0);
;     }
; #pragma unroll
;     for (int mt = 0; mt < 2; ++mt)
; #pragma unroll
;       for (int jj = 0; jj < 4; ++jj) {
;         const int tok = mt * 16 + fq * 4 + jj, row = row0 + tok;
;         float yv[4], sm_ = 0.f;
; #pragma unroll
;         for (int nt = 0; nt < 4; ++nt) { yv[nt] = ys[tok * 516 + w * 64 + nt * 16 + fr]; sm_ += yv[nt]; }
;         const float mean = row16_sum(sm_) * (1.f / 64.f);
;         float vs = 0.f;
; #pragma unroll
;         for (int nt = 0; nt < 4; ++nt) { yv[nt] -= mean; vs += yv[nt] * yv[nt]; }
;         const float rs = rsqrtf(row16_sum(vs) * (1.f / 64.f) + 64e-5f);
;         const float2 sb2 = *(const float2*)(P_SBON + ((size_t)row * 8 + w) * 2);
;         const float sbs = sb2.x + sb2.y;
; #pragma unroll
;         for (int nt = 0; nt < 4; ++nt) {
;           const float vv = bf2f(vt[tok * 520 + w * 64 + nt * 16 + fr]);
;           const float o = (yv[nt] * rs * lng[nt] + lnb[nt] + sbs * vv) * acc[mt][nt][jj];
.LBB0_826:
	s_waitcnt lgkmcnt(0)
	s_barrier
	ds_read_b128 v[80:83], v157
	ds_read_b128 v[84:87], v157 offset:64
	v_or_b32_e32 v138, s39, v149
	v_ashrrev_i32_e32 v139, 31, v138
	s_waitcnt lgkmcnt(1)
	v_mfma_f32_16x16x32_bf16 v[88:91], v[80:83], v[76:79], 0
	v_add_u32_e32 v120, 0xb400, v158
	v_add_u32_e32 v166, 0xb400, v160
	v_mfma_f32_16x16x32_bf16 v[92:95], v[80:83], v[56:59], 0
	v_mfma_f32_16x16x32_bf16 v[96:99], v[80:83], v[36:39], 0
	v_mfma_f32_16x16x32_bf16 v[100:103], v[80:83], v[16:19], 0
	v_lshlrev_b64 v[80:81], 6, v[138:139]
	v_lshl_add_u64 v[80:81], v[130:131], 0, v[80:81]
	global_load_dwordx2 v[140:141], v[80:81], off
	v_mov_b32_e32 v250, v80
	v_mov_b32_e32 v251, v81
	global_load_dwordx2 v[252:253], v[80:81], off offset:64
	global_load_dwordx2 v[254:255], v[80:81], off offset:128
	s_waitcnt lgkmcnt(0)
	v_mfma_f32_16x16x32_bf16 v[88:91], v[84:87], v[72:75], v[88:91]
	ds_read_b128 v[104:107], v157 offset:128
	ds_read_b128 v[108:111], v157 offset:192
	ds_read_b128 v[112:115], v157 offset:256
	ds_read_b128 v[116:119], v157 offset:320
	v_mov_b64_e32 v[82:83], s[6:7]
	v_mfma_f32_16x16x32_bf16 v[92:95], v[84:87], v[52:55], v[92:95]
	v_mov_b64_e32 v[80:81], s[4:5]
	v_lshlrev_b64 v[138:139], 11, v[138:139]
	v_lshl_add_u64 v[138:139], v[132:133], 0, v[138:139]
	v_mfma_f32_16x16x32_bf16 v[96:99], v[84:87], v[32:35], v[96:99]
	s_waitcnt vmcnt(2)
	v_add_f32_e32 v140, v140, v141
	v_mfma_f32_16x16x32_bf16 v[84:87], v[84:87], v[12:15], v[100:103]
	ds_read_u16 v168, v159 offset:12800
	ds_read_u16 v169, v159 offset:12832
	ds_read_u16 v170, v159 offset:12864
	ds_read_u16 v171, v159 offset:12896
	ds_read_u16 v172, v161 offset:12800
	ds_read_u16 v173, v161 offset:12832
	ds_read_u16 v174, v161 offset:12864
	ds_read_u16 v175, v161 offset:12896
	ds_read2_b32 v[100:101], v120 offset1:16
	ds_read2_b32 v[102:103], v120 offset0:32 offset1:48
	ds_read2_b32 v[164:165], v166 offset1:16
	ds_read2_b32 v[166:167], v166 offset0:32 offset1:48
	s_waitcnt lgkmcnt(10)
	v_lshlrev_b32_e32 v176, 16, v169
	v_mfma_f32_16x16x32_bf16 v[88:91], v[104:107], v[68:71], v[88:91]
	s_waitcnt lgkmcnt(2)
	v_mov_b32_e32 v169, v102
	v_add_f32_e32 v177, 0, v100
	v_lshlrev_b32_e32 v120, 16, v168
	v_mfma_f32_16x16x32_bf16 v[92:95], v[104:107], v[48:51], v[92:95]
	v_mov_b32_e32 v168, v103
	v_mfma_f32_16x16x32_bf16 v[96:99], v[104:107], v[28:31], v[96:99]
	v_mfma_f32_16x16x32_bf16 v[84:87], v[104:107], v[8:11], v[84:87]
	s_waitcnt lgkmcnt(1)
	v_add_f32_e32 v104, 0, v164
	v_add_f32_e32 v105, v177, v101
	v_add_f32_e32 v104, v104, v165
	v_add_f32_e32 v102, v105, v102
	s_waitcnt lgkmcnt(0)
	v_add_f32_e32 v104, v104, v166
	v_mfma_f32_16x16x32_bf16 v[88:91], v[108:111], v[64:67], v[88:91]
	v_add_f32_e32 v102, v102, v103
	v_add_f32_e32 v103, v104, v167
	v_mov_b32_e32 v106, v167
	v_mfma_f32_16x16x32_bf16 v[92:95], v[108:111], v[44:47], v[92:95]
	v_add_f32_dpp v102, v102, v102 row_ror:8 row_mask:0xf bank_mask:0xf bound_ctrl:1
	v_add_f32_dpp v103, v103, v103 row_ror:8 row_mask:0xf bank_mask:0xf bound_ctrl:1
	v_mov_b32_e32 v107, v166
	v_mfma_f32_16x16x32_bf16 v[96:99], v[108:111], v[24:27], v[96:99]
	v_add_f32_dpp v102, v102, v102 row_ror:4 row_mask:0xf bank_mask:0xf bound_ctrl:1
	v_add_f32_dpp v103, v103, v103 row_ror:4 row_mask:0xf bank_mask:0xf bound_ctrl:1
	v_mfma_f32_16x16x32_bf16 v[84:87], v[108:111], v[4:7], v[84:87]
	v_add_f32_dpp v102, v102, v102 row_ror:2 row_mask:0xf bank_mask:0xf bound_ctrl:1
	v_add_f32_dpp v103, v103, v103 row_ror:2 row_mask:0xf bank_mask:0xf bound_ctrl:1
	v_mfma_f32_16x16x32_bf16 v[88:91], v[112:115], v[60:63], v[88:91]
	v_add_f32_dpp v102, v102, v102 row_ror:1 row_mask:0xf bank_mask:0xf bound_ctrl:1
	v_add_f32_dpp v103, v103, v103 row_ror:1 row_mask:0xf bank_mask:0xf bound_ctrl:1
	v_mul_f32_e32 v108, 0x3c800000, v102
	v_mfma_f32_16x16x32_bf16 v[92:95], v[112:115], v[40:43], v[92:95]
	v_mul_f32_e32 v110, 0x3c800000, v103
	v_pk_add_f32 v[166:167], v[100:101], v[108:109] op_sel_hi:[1,0] neg_lo:[0,1] neg_hi:[0,1]
	v_pk_add_f32 v[164:165], v[164:165], v[110:111] op_sel_hi:[1,0] neg_lo:[0,1] neg_hi:[0,1]
	v_mfma_f32_16x16x32_bf16 v[102:105], v[112:115], v[20:23], v[96:99]
	v_pk_add_f32 v[108:109], v[168:169], v[108:109] op_sel_hi:[1,0] neg_lo:[0,1] neg_hi:[0,1]
	v_pk_add_f32 v[110:111], v[106:107], v[110:111] op_sel_hi:[1,0] neg_lo:[0,1] neg_hi:[0,1]
	v_pk_mul_f32 v[106:107], v[166:167], v[166:167]
	v_mfma_f32_16x16x32_bf16 v[84:87], v[112:115], v[0:3], v[84:87]
	v_mul_f32_e64 v114, v164, v164
	v_mul_f32_e64 v115, v165, v165
	v_pk_mul_f32 v[112:113], v[108:109], v[108:109]
	v_pk_mul_f32 v[168:169], v[110:111], v[110:111]
	v_mfma_f32_16x16x32_bf16 v[98:101], v[116:119], v[80:83], v[88:91]
	s_nop 2
	v_mov_b32_e32 v88, v114
	v_mov_b32_e32 v89, v106
	v_mov_b32_e32 v106, v115
	v_mfma_f32_16x16x32_bf16 v[94:97], v[116:119], v[80:83], v[92:95]
	v_add_f32_e64 v88, v88, v106
	v_add_f32_e64 v89, v89, v107
	v_mov_b64_e32 v[106:107], s[18:19]
	v_mfma_f32_16x16x32_bf16 v[90:93], v[116:119], v[80:83], v[102:105]
	s_nop 2
	v_mov_b32_e32 v102, v169
	v_mov_b32_e32 v103, v113
	v_pk_add_f32 v[102:103], v[102:103], v[88:89]
	v_mov_b32_e32 v169, v112
	v_mfma_f32_16x16x32_bf16 v[86:89], v[116:119], v[80:83], v[84:87]
	v_lshlrev_b32_e32 v104, 16, v171
	v_add_u32_e32 v116, 0xbc00, v160
	s_nop 0
	v_pk_add_f32 v[84:85], v[168:169], v[102:103]
	v_mov_b32_e32 v103, v121
	v_mov_b32_e32 v102, v121
	s_nop 0
	v_mov_b32_dpp v103, v85 row_ror:8 row_mask:0xf bank_mask:0xf
	v_mov_b32_dpp v102, v84 row_ror:8 row_mask:0xf bank_mask:0xf
	v_pk_add_f32 v[84:85], v[84:85], v[102:103]
	v_mov_b32_e32 v103, v121
	v_mov_b32_e32 v102, v121
	s_nop 0
	v_mov_b32_dpp v103, v85 row_ror:4 row_mask:0xf bank_mask:0xf
; __device__ __forceinline__ float bf2f(bf16_t b) { return __uint_as_float(((unsigned)b) << 16); }
; __device__ __forceinline__ void post_phase(PREF p, char* smem, const int wid_u, const int tile_first, const int tile_end, const int tile_step) {
;     ...
; #pragma unroll
;     for (int mt = 0; mt < 2; ++mt)
; #pragma unroll
;       for (int jj = 0; jj < 4; ++jj) {
;         const int tok = mt * 16 + fq * 4 + jj, row = row0 + tok;
;         float yv[4], sm_ = 0.f;
; #pragma unroll
;         for (int nt = 0; nt < 4; ++nt) { yv[nt] = ys[tok * 516 + w * 64 + nt * 16 + fr]; sm_ += yv[nt]; }
;         const float mean = row16_sum(sm_) * (1.f / 64.f);
;         float vs = 0.f;
; #pragma unroll
;         for (int nt = 0; nt < 4; ++nt) { yv[nt] -= mean; vs += yv[nt] * yv[nt]; }
;         const float rs = rsqrtf(row16_sum(vs) * (1.f / 64.f) + 64e-5f);
;         const float2 sb2 = *(const float2*)(P_SBON + ((size_t)row * 8 + w) * 2);
;         const float sbs = sb2.x + sb2.y;
; #pragma unroll
;         for (int nt = 0; nt < 4; ++nt) {
;           const float vv = bf2f(vt[tok * 520 + w * 64 + nt * 16 + fr]);
;           const float o = (yv[nt] * rs * lng[nt] + lnb[nt] + sbs * vv) * acc[mt][nt][jj];
;           mo[(size_t)row * D + 512 + w * 64 + nt * 16 + fr] = (bf16_t)(cvt_pk_bf16(o, 0.f) & 0xffff);
;         }
;       }
	v_mov_b32_dpp v102, v84 row_ror:4 row_mask:0xf bank_mask:0xf
	v_pk_add_f32 v[84:85], v[84:85], v[102:103]
	v_mov_b32_e32 v103, v121
	v_mov_b32_e32 v102, v121
	s_nop 0
	v_mov_b32_dpp v103, v85 row_ror:2 row_mask:0xf bank_mask:0xf
	v_mov_b32_dpp v102, v84 row_ror:2 row_mask:0xf bank_mask:0xf
	v_pk_add_f32 v[84:85], v[84:85], v[102:103]
	v_mov_b32_e32 v103, v121
	v_mov_b32_e32 v102, v121
	s_nop 0
	v_mov_b32_dpp v103, v85 row_ror:1 row_mask:0xf bank_mask:0xf
	v_mov_b32_dpp v102, v84 row_ror:1 row_mask:0xf bank_mask:0xf
	v_pk_add_f32 v[84:85], v[84:85], v[102:103]
	v_lshlrev_b32_e32 v103, 16, v170
	v_pk_fma_f32 v[84:85], v[84:85], s[16:17], v[106:107] op_sel_hi:[1,0,0]
	s_nop 0
	v_mul_f32_e32 v102, 0x4b800000, v85
	v_cmp_gt_f32_e32 vcc, s38, v85
	s_nop 1
	v_cndmask_b32_e32 v85, v85, v102, vcc
	v_rsq_f32_e32 v85, v85
	v_or_b32_e32 v102, s39, v150
	v_mul_f32_e32 v105, 0x45800000, v85
	v_cndmask_b32_e32 v85, v85, v105, vcc
	v_mul_f32_e32 v105, v166, v85
	v_fma_f32 v105, v129, v105, v145
	v_fmac_f32_e32 v105, v140, v120
	v_mul_f32_e32 v98, v98, v105
	v_cvt_pk_bf16_f32 v98, v98, s0
	global_store_short v[138:139], v98, off
	v_mul_f32_e32 v98, v167, v85
	v_fma_f32 v98, v142, v98, v146
	v_fmac_f32_e32 v98, v140, v176
	v_mul_f32_e32 v94, v94, v98
	v_cvt_pk_bf16_f32 v94, v94, s0
	global_store_short v[138:139], v94, off offset:32
	v_mul_f32_e32 v94, v109, v85
	v_mul_f32_e32 v85, v108, v85
	v_fma_f32 v94, v143, v94, v147
	v_fma_f32 v85, v144, v85, v148
	v_fmac_f32_e32 v94, v140, v103
	v_fmac_f32_e32 v85, v140, v104
	v_mul_f32_e32 v90, v90, v94
	v_mul_f32_e32 v85, v86, v85
	v_ashrrev_i32_e32 v103, 31, v102
	v_cvt_pk_bf16_f32 v90, v90, s0
	v_cvt_pk_bf16_f32 v85, v85, s0
	v_lshlrev_b64 v[104:105], 6, v[102:103]
	global_store_short v[138:139], v90, off offset:64
	global_store_short v[138:139], v85, off offset:96
	v_lshl_add_u64 v[104:105], v[130:131], 0, v[104:105]
	v_mul_f32_e32 v85, 0x4b800000, v84
	v_cmp_gt_f32_e32 vcc, s38, v84
	v_lshlrev_b64 v[102:103], 11, v[102:103]
	v_lshlrev_b32_e32 v90, 16, v172
	v_cndmask_b32_e32 v84, v84, v85, vcc
	v_rsq_f32_e32 v86, v84
	v_lshl_add_u64 v[84:85], v[132:133], 0, v[102:103]
	v_lshlrev_b32_e32 v94, 16, v173
	v_add_u32_e32 v120, 0xc400, v160
	v_mul_f32_e32 v98, 0x45800000, v86
	v_cndmask_b32_e32 v86, v86, v98, vcc
	v_mul_f32_e32 v98, v164, v86
	v_fma_f32 v98, v129, v98, v145
	v_mul_f32_e32 v102, v165, v86
	s_waitcnt vmcnt(5)
	v_add_f32_e32 v103, v252, v253
	global_load_dwordx2 v[252:253], v[250:251], off offset:192
	v_fmac_f32_e32 v98, v103, v90
	v_mul_f32_e32 v90, v99, v98
	v_cvt_pk_bf16_f32 v90, v90, s0
	global_store_short v[84:85], v90, off
	v_fma_f32 v90, v142, v102, v146
	v_fmac_f32_e32 v90, v103, v94
	v_mul_f32_e32 v90, v95, v90
	v_cvt_pk_bf16_f32 v90, v90, s0
	v_mul_f32_e32 v94, v111, v86
	global_store_short v[84:85], v90, off offset:32
	v_lshlrev_b32_e32 v90, 16, v174
	v_fma_f32 v94, v143, v94, v147
	v_fmac_f32_e32 v94, v103, v90
	v_mul_f32_e32 v90, v91, v94
	v_cvt_pk_bf16_f32 v90, v90, s0
	v_mul_f32_e32 v86, v110, v86
	global_store_short v[84:85], v90, off offset:64
	v_lshlrev_b32_e32 v90, 16, v175
	v_fma_f32 v86, v144, v86, v148
	v_fmac_f32_e32 v86, v103, v90
	v_mul_f32_e32 v86, v87, v86
	v_or_b32_e32 v90, s39, v151
	v_cvt_pk_bf16_f32 v86, v86, s0
	v_ashrrev_i32_e32 v91, 31, v90
	global_store_short v[84:85], v86, off offset:96
	v_lshlrev_b64 v[84:85], 6, v[90:91]
	v_lshl_add_u64 v[84:85], v[130:131], 0, v[84:85]
	ds_read_b128 v[108:111], v157 offset:6400
	ds_read_b128 v[112:115], v157 offset:6464
	ds_read_b128 v[102:105], v157 offset:6528
	ds_read_b128 v[84:87], v157 offset:6592
	ds_read_u16 v164, v161 offset:13840
	ds_read_u16 v165, v161 offset:13872
	ds_read_u16 v180, v161 offset:13904
	ds_read_u16 v181, v161 offset:13936
	ds_read_u16 v182, v161 offset:14880
	ds_read_u16 v183, v161 offset:14912
	ds_read_u16 v184, v161 offset:14944
	ds_read_u16 v185, v161 offset:14976
	ds_read2_b32 v[98:99], v116 offset0:4 offset1:20
	ds_read2_b32 v[168:169], v116 offset0:36 offset1:52
	ds_read2_b32 v[170:171], v120 offset0:8 offset1:24
	ds_read2_b32 v[172:173], v120 offset0:40 offset1:56
	s_waitcnt lgkmcnt(14)
	v_mfma_f32_16x16x32_bf16 v[116:119], v[108:111], v[76:79], 0
	s_waitcnt lgkmcnt(3)
	v_add_f32_e32 v120, 0, v98
	v_add_f32_e32 v120, v120, v99
	s_waitcnt lgkmcnt(1)
	v_add_f32_e32 v176, 0, v170
	v_mfma_f32_16x16x32_bf16 v[138:141], v[108:111], v[56:59], 0
	v_add_f32_e32 v176, v176, v171
	v_mov_b32_e32 v175, v168
	v_add_f32_e32 v120, v120, v168
	s_waitcnt lgkmcnt(0)
	v_add_f32_e32 v168, v176, v172
	v_lshlrev_b32_e32 v186, 16, v164
	v_lshlrev_b32_e32 v187, 16, v165
	v_mfma_f32_16x16x32_bf16 v[164:167], v[108:111], v[36:39], 0
	v_add_f32_e32 v120, v120, v169
	v_add_f32_e32 v168, v168, v173
	v_mov_b32_e32 v174, v169
	v_mfma_f32_16x16x32_bf16 v[108:111], v[108:111], v[16:19], 0
	v_add_f32_dpp v120, v120, v120 row_ror:8 row_mask:0xf bank_mask:0xf bound_ctrl:1
	v_add_f32_dpp v168, v168, v168 row_ror:8 row_mask:0xf bank_mask:0xf bound_ctrl:1
	v_lshlrev_b64 v[90:91], 11, v[90:91]
	v_mfma_f32_16x16x32_bf16 v[116:119], v[112:115], v[72:75], v[116:119]
	v_add_f32_dpp v120, v120, v120 row_ror:4 row_mask:0xf bank_mask:0xf bound_ctrl:1
	v_add_f32_dpp v168, v168, v168 row_ror:4 row_mask:0xf bank_mask:0xf bound_ctrl:1
	v_lshl_add_u64 v[90:91], v[132:133], 0, v[90:91]
	v_mfma_f32_16x16x32_bf16 v[138:141], v[112:115], v[52:55], v[138:141]
	v_add_f32_dpp v120, v120, v120 row_ror:2 row_mask:0xf bank_mask:0xf bound_ctrl:1
	v_add_f32_dpp v168, v168, v168 row_ror:2 row_mask:0xf bank_mask:0xf bound_ctrl:1
	v_mfma_f32_16x16x32_bf16 v[164:167], v[112:115], v[32:35], v[164:167]
	v_mfma_f32_16x16x32_bf16 v[108:111], v[112:115], v[12:15], v[108:111]
	v_add_f32_dpp v112, v120, v120 row_ror:1 row_mask:0xf bank_mask:0xf bound_ctrl:1
	v_add_f32_dpp v113, v168, v168 row_ror:1 row_mask:0xf bank_mask:0xf bound_ctrl:1
	v_mul_f32_e32 v120, 0x3c800000, v112
	v_mul_f32_e32 v168, 0x3c800000, v113
	v_pk_add_f32 v[98:99], v[98:99], v[120:121] op_sel_hi:[1,0] neg_lo:[0,1] neg_hi:[0,1]
	v_mfma_f32_16x16x32_bf16 v[112:115], v[102:105], v[68:71], v[116:119]
	v_add_f32_e64 v174, v174, -v120
	v_add_f32_e64 v175, v175, -v120
	v_pk_mul_f32 v[176:177], v[98:99], v[98:99]
	v_pk_mul_f32 v[178:179], v[174:175], v[174:175]
	v_mfma_f32_16x16x32_bf16 v[116:119], v[102:105], v[48:51], v[138:141]
	s_waitcnt vmcnt(9)
; __device__ __forceinline__ float bf2f(bf16_t b) { return __uint_as_float(((unsigned)b) << 16); }
; __device__ __forceinline__ void post_phase(PREF p, char* smem, const int wid_u, const int tile_first, const int tile_end, const int tile_step) {
;     ...
; #pragma unroll
;     for (int mt = 0; mt < 2; ++mt)
; #pragma unroll
;       for (int jj = 0; jj < 4; ++jj) {
;         const int tok = mt * 16 + fq * 4 + jj, row = row0 + tok;
;         float yv[4], sm_ = 0.f;
; #pragma unroll
;         for (int nt = 0; nt < 4; ++nt) { yv[nt] = ys[tok * 516 + w * 64 + nt * 16 + fr]; sm_ += yv[nt]; }
;         const float mean = row16_sum(sm_) * (1.f / 64.f);
;         float vs = 0.f;
; #pragma unroll
;         for (int nt = 0; nt < 4; ++nt) { yv[nt] -= mean; vs += yv[nt] * yv[nt]; }
;         const float rs = rsqrtf(row16_sum(vs) * (1.f / 64.f) + 64e-5f);
;         const float2 sb2 = *(const float2*)(P_SBON + ((size_t)row * 8 + w) * 2);
;         const float sbs = sb2.x + sb2.y;
; #pragma unroll
;         for (int nt = 0; nt < 4; ++nt) {
;           const float vv = bf2f(vt[tok * 520 + w * 64 + nt * 16 + fr]);
;           const float o = (yv[nt] * rs * lng[nt] + lnb[nt] + sbs * vv) * acc[mt][nt][jj];
;           mo[(size_t)row * D + 512 + w * 64 + nt * 16 + fr] = (bf16_t)(cvt_pk_bf16(o, 0.f) & 0xffff);
;         }
;       }
	v_add_f32_e32 v120, v254, v255
	global_load_dwordx2 v[254:255], v[250:251], off offset:1024
	v_pk_add_f32 v[94:95], v[170:171], v[168:169] op_sel_hi:[1,0] neg_lo:[0,1] neg_hi:[0,1]
	v_mov_b32_e32 v140, v173
	v_mov_b32_e32 v141, v172
	v_pk_mul_f32 v[138:139], v[94:95], v[94:95]
	v_pk_add_f32 v[168:169], v[140:141], v[168:169] op_sel_hi:[1,0] neg_lo:[0,1] neg_hi:[0,1]
	v_mov_b32_e32 v170, v138
	v_pk_mul_f32 v[140:141], v[168:169], v[168:169]
	v_mov_b32_e32 v171, v176
	v_mov_b32_e32 v176, v139
	v_pk_add_f32 v[138:139], v[170:171], v[176:177]
	v_mov_b32_e32 v170, v141
	v_mov_b32_e32 v171, v179
	v_pk_add_f32 v[138:139], v[170:171], v[138:139]
	v_mov_b32_e32 v141, v178
	v_pk_add_f32 v[138:139], v[140:141], v[138:139]
	v_mov_b32_e32 v141, v121
	v_mov_b32_e32 v140, v121
	s_nop 0
	v_mov_b32_dpp v141, v139 row_ror:8 row_mask:0xf bank_mask:0xf
	v_mov_b32_dpp v140, v138 row_ror:8 row_mask:0xf bank_mask:0xf
	v_pk_add_f32 v[138:139], v[138:139], v[140:141]
	v_mov_b32_e32 v141, v121
	v_mov_b32_e32 v140, v121
	s_nop 0
	v_mov_b32_dpp v141, v139 row_ror:4 row_mask:0xf bank_mask:0xf
	v_mov_b32_dpp v140, v138 row_ror:4 row_mask:0xf bank_mask:0xf
	v_pk_add_f32 v[138:139], v[138:139], v[140:141]
	v_mov_b32_e32 v141, v121
	v_mov_b32_e32 v140, v121
	s_nop 0
	v_mov_b32_dpp v141, v139 row_ror:2 row_mask:0xf bank_mask:0xf
	v_mov_b32_dpp v140, v138 row_ror:2 row_mask:0xf bank_mask:0xf
	v_pk_add_f32 v[138:139], v[138:139], v[140:141]
	v_mov_b32_e32 v141, v121
	v_mov_b32_e32 v140, v121
	s_nop 0
	v_mov_b32_dpp v141, v139 row_ror:1 row_mask:0xf bank_mask:0xf
	v_mov_b32_dpp v140, v138 row_ror:1 row_mask:0xf bank_mask:0xf
	v_pk_add_f32 v[138:139], v[138:139], v[140:141]
	v_lshlrev_b32_e32 v140, 16, v180
	v_pk_fma_f32 v[170:171], v[138:139], s[16:17], v[106:107] op_sel_hi:[1,0,0]
	v_lshlrev_b32_e32 v141, 16, v181
	v_mul_f32_e32 v138, 0x4b800000, v171
	v_cmp_gt_f32_e32 vcc, s38, v171
	s_nop 1
	v_cndmask_b32_e32 v138, v171, v138, vcc
	v_rsq_f32_e32 v139, v138
	v_or_b32_e32 v138, s39, v152
	v_mul_f32_e32 v171, 0x45800000, v139
	v_cndmask_b32_e32 v139, v139, v171, vcc
	v_mul_f32_e32 v98, v98, v139
	v_fma_f32 v98, v129, v98, v145
	v_fmac_f32_e32 v98, v120, v186
	v_mul_f32_e32 v98, v100, v98
	v_cvt_pk_bf16_f32 v98, v98, s0
	global_store_short v[90:91], v98, off
	v_mul_f32_e32 v98, v99, v139
	v_fma_f32 v98, v142, v98, v146
	v_fmac_f32_e32 v98, v120, v187
	v_mul_f32_e32 v96, v96, v98
	v_cvt_pk_bf16_f32 v96, v96, s0
	global_store_short v[90:91], v96, off offset:32
	v_mul_f32_e32 v96, v175, v139
	v_fma_f32 v96, v143, v96, v147
	v_fmac_f32_e32 v96, v120, v140
	v_mul_f32_e32 v92, v92, v96
	v_cvt_pk_bf16_f32 v92, v92, s0
	global_store_short v[90:91], v92, off offset:64
	v_mul_f32_e32 v92, v174, v139
	v_fma_f32 v92, v144, v92, v148
	v_fmac_f32_e32 v92, v120, v141
	v_mul_f32_e32 v88, v88, v92
	v_cvt_pk_bf16_f32 v88, v88, s0
	v_ashrrev_i32_e32 v139, 31, v138
	global_store_short v[90:91], v88, off offset:96
	v_lshlrev_b64 v[90:91], 6, v[138:139]
	v_lshl_add_u64 v[90:91], v[130:131], 0, v[90:91]
	v_mul_f32_e32 v88, 0x4b800000, v170
	v_cmp_gt_f32_e32 vcc, s38, v170
	v_lshlrev_b32_e32 v92, 16, v182
	v_lshlrev_b64 v[98:99], 11, v[138:139]
	v_cndmask_b32_e32 v88, v170, v88, vcc
	v_rsq_f32_e32 v88, v88
	v_lshl_add_u64 v[98:99], v[132:133], 0, v[98:99]
	v_or_b32_e32 v100, s39, v153
	v_mfma_f32_16x16x32_bf16 v[138:141], v[102:105], v[28:31], v[164:167]
	v_mul_f32_e32 v96, 0x45800000, v88
	v_cndmask_b32_e32 v88, v88, v96, vcc
	v_add_u32_e32 v120, 0xb400, v162
	v_mfma_f32_16x16x32_bf16 v[102:105], v[102:105], v[8:11], v[108:111]
	v_add_u32_e32 v166, 0xbc00, v162
	s_waitcnt vmcnt(9)
	v_add_f32_e32 v90, v252, v253
	global_load_dwordx2 v[252:253], v[250:251], off offset:1088
	v_mul_f32_e32 v91, v94, v88
	v_fma_f32 v91, v129, v91, v145
	v_fmac_f32_e32 v91, v90, v92
	v_mul_f32_e32 v91, v101, v91
	v_cvt_pk_bf16_f32 v91, v91, s0
	v_mul_f32_e32 v92, v95, v88
	global_store_short v[98:99], v91, off
	v_lshlrev_b32_e32 v91, 16, v183
	v_fma_f32 v92, v142, v92, v146
	v_fmac_f32_e32 v92, v90, v91
	v_mul_f32_e32 v91, v97, v92
	v_cvt_pk_bf16_f32 v91, v91, s0
	v_mul_f32_e32 v92, v169, v88
	global_store_short v[98:99], v91, off offset:32
	v_lshlrev_b32_e32 v91, 16, v184
	v_fma_f32 v92, v143, v92, v147
	v_fmac_f32_e32 v92, v90, v91
	v_mul_f32_e32 v91, v93, v92
	v_cvt_pk_bf16_f32 v91, v91, s0
	v_mul_f32_e32 v88, v168, v88
	global_store_short v[98:99], v91, off offset:64
	v_lshlrev_b32_e32 v91, 16, v185
	v_fma_f32 v88, v144, v88, v148
	v_fmac_f32_e32 v88, v90, v91
	v_mul_f32_e32 v88, v89, v88
	v_cvt_pk_bf16_f32 v88, v88, s0
	v_ashrrev_i32_e32 v101, 31, v100
	global_store_short v[98:99], v88, off offset:96
	v_lshlrev_b64 v[88:89], 6, v[100:101]
	v_lshl_add_u64 v[88:89], v[130:131], 0, v[88:89]
	ds_read_b128 v[92:95], v157 offset:6656
	ds_read_b128 v[96:99], v157 offset:6720
	v_mfma_f32_16x16x32_bf16 v[108:111], v[84:87], v[44:47], v[116:119]
	ds_read_u16 v167, v161 offset:28400
	ds_read_u16 v168, v161 offset:28432
	ds_read_u16 v169, v161 offset:28464
	ds_read_u16 v170, v161 offset:28496
	ds_read_u16 v171, v161 offset:29440
	ds_read_u16 v172, v161 offset:29472
	ds_read_u16 v173, v161 offset:29504
	ds_read_u16 v174, v161 offset:29536
	ds_read2_b32 v[116:117], v120 offset1:16
	v_lshlrev_b64 v[100:101], 11, v[100:101]
	s_waitcnt lgkmcnt(7)
	v_lshlrev_b32_e32 v168, 16, v168
	v_mfma_f32_16x16x32_bf16 v[88:91], v[84:87], v[64:67], v[112:115]
	s_waitcnt lgkmcnt(0)
	v_add_f32_e32 v175, 0, v116
	v_add_f32_e32 v175, v175, v117
	v_mfma_f32_16x16x32_bf16 v[112:115], v[84:87], v[24:27], v[138:141]
	ds_read2_b32 v[118:119], v120 offset0:32 offset1:48
	s_nop 1
	ds_read2_b32 v[138:139], v166 offset0:4 offset1:20
	ds_read2_b32 v[140:141], v166 offset0:36 offset1:52
	v_lshlrev_b32_e32 v120, 16, v167
	s_waitcnt lgkmcnt(2)
; __device__ __forceinline__ float bf2f(bf16_t b) { return __uint_as_float(((unsigned)b) << 16); }
; __device__ __forceinline__ void post_phase(PREF p, char* smem, const int wid_u, const int tile_first, const int tile_end, const int tile_step) {
;     ...
; #pragma unroll
;     for (int mt = 0; mt < 2; ++mt)
; #pragma unroll
;       for (int jj = 0; jj < 4; ++jj) {
;         const int tok = mt * 16 + fq * 4 + jj, row = row0 + tok;
;         float yv[4], sm_ = 0.f;
; #pragma unroll
;         for (int nt = 0; nt < 4; ++nt) { yv[nt] = ys[tok * 516 + w * 64 + nt * 16 + fr]; sm_ += yv[nt]; }
;         const float mean = row16_sum(sm_) * (1.f / 64.f);
;         float vs = 0.f;
; #pragma unroll
;         for (int nt = 0; nt < 4; ++nt) { yv[nt] -= mean; vs += yv[nt] * yv[nt]; }
;         const float rs = rsqrtf(row16_sum(vs) * (1.f / 64.f) + 64e-5f);
;         const float2 sb2 = *(const float2*)(P_SBON + ((size_t)row * 8 + w) * 2);
;         const float sbs = sb2.x + sb2.y;
; #pragma unroll
;         for (int nt = 0; nt < 4; ++nt) {
;           const float vv = bf2f(vt[tok * 520 + w * 64 + nt * 16 + fr]);
;           const float o = (yv[nt] * rs * lng[nt] + lnb[nt] + sbs * vv) * acc[mt][nt][jj];
;           mo[(size_t)row * D + 512 + w * 64 + nt * 16 + fr] = (bf16_t)(cvt_pk_bf16(o, 0.f) & 0xffff);
;         }
;       }
	v_mov_b32_e32 v167, v118
	v_mfma_f32_16x16x32_bf16 v[84:87], v[84:87], v[4:7], v[102:105]
	s_waitcnt lgkmcnt(1)
	v_add_f32_e32 v176, 0, v138
	v_add_f32_e32 v118, v175, v118
	v_mov_b32_e32 v166, v119
	v_lshl_add_u64 v[104:105], v[132:133], 0, v[100:101]
	v_mfma_f32_16x16x32_bf16 v[100:103], v[92:95], v[40:43], v[108:111]
	v_mfma_f32_16x16x32_bf16 v[108:111], v[92:95], v[20:23], v[112:115]
	s_nop 2
	v_add_f32_e32 v112, v176, v139
	s_waitcnt lgkmcnt(0)
	v_add_f32_e32 v175, v112, v140
	v_mfma_f32_16x16x32_bf16 v[112:115], v[92:95], v[0:3], v[84:87]
	s_nop 2
	v_add_f32_e32 v84, v118, v119
	v_mfma_f32_16x16x32_bf16 v[88:91], v[92:95], v[60:63], v[88:91]
	v_add_f32_e32 v85, v175, v141
	v_add_f32_dpp v84, v84, v84 row_ror:8 row_mask:0xf bank_mask:0xf bound_ctrl:1
	s_waitcnt vmcnt(9)
	v_add_f32_e32 v119, v254, v255
	global_load_dwordx2 v[254:255], v[250:251], off offset:1152
	v_add_f32_dpp v84, v84, v84 row_ror:4 row_mask:0xf bank_mask:0xf bound_ctrl:1
	v_add_f32_dpp v118, v85, v85 row_ror:8 row_mask:0xf bank_mask:0xf bound_ctrl:1
	v_mfma_f32_16x16x32_bf16 v[88:91], v[96:99], v[80:83], v[88:91]
	v_add_f32_dpp v84, v84, v84 row_ror:2 row_mask:0xf bank_mask:0xf bound_ctrl:1
	s_nop 1
	v_add_f32_dpp v84, v84, v84 row_ror:1 row_mask:0xf bank_mask:0xf bound_ctrl:1
	v_mfma_f32_16x16x32_bf16 v[92:95], v[96:99], v[80:83], v[100:103]
	s_nop 2
	v_mul_f32_e32 v100, 0x3c800000, v84
	v_mfma_f32_16x16x32_bf16 v[84:87], v[96:99], v[80:83], v[108:111]
	v_add_f32_e64 v102, v116, -v100
	v_add_f32_e64 v103, v117, -v100
	v_pk_add_f32 v[100:101], v[166:167], v[100:101] op_sel_hi:[1,0] neg_lo:[0,1] neg_hi:[0,1]
	v_mfma_f32_16x16x32_bf16 v[80:83], v[96:99], v[80:83], v[112:115]
	v_add_f32_dpp v96, v118, v118 row_ror:4 row_mask:0xf bank_mask:0xf bound_ctrl:1
	v_pk_mul_f32 v[108:109], v[102:103], v[102:103]
	v_pk_mul_f32 v[110:111], v[100:101], v[100:101]
	v_add_f32_dpp v96, v96, v96 row_ror:2 row_mask:0xf bank_mask:0xf bound_ctrl:1
	v_mov_b32_e32 v114, v141
	v_mov_b32_e32 v115, v140
	v_add_f32_dpp v96, v96, v96 row_ror:1 row_mask:0xf bank_mask:0xf bound_ctrl:1
	v_mul_f32_e32 v96, 0x3c800000, v96
	v_pk_add_f32 v[98:99], v[138:139], v[96:97] op_sel_hi:[1,0] neg_lo:[0,1] neg_hi:[0,1]
	v_pk_add_f32 v[96:97], v[114:115], v[96:97] op_sel_hi:[1,0] neg_lo:[0,1] neg_hi:[0,1]
	v_pk_mul_f32 v[112:113], v[98:99], v[98:99]
	v_pk_mul_f32 v[114:115], v[96:97], v[96:97]
	v_mov_b32_e32 v116, v112
	v_mov_b32_e32 v117, v108
	v_mov_b32_e32 v108, v113
	v_pk_add_f32 v[108:109], v[116:117], v[108:109]
	v_mov_b32_e32 v112, v115
	v_mov_b32_e32 v113, v111
	v_pk_add_f32 v[108:109], v[112:113], v[108:109]
	v_mov_b32_e32 v115, v110
	v_pk_add_f32 v[108:109], v[114:115], v[108:109]
	v_mov_b32_e32 v111, v121
	v_mov_b32_e32 v110, v121
	v_lshlrev_b32_e32 v112, 16, v170
	v_mov_b32_dpp v111, v109 row_ror:8 row_mask:0xf bank_mask:0xf
	v_mov_b32_dpp v110, v108 row_ror:8 row_mask:0xf bank_mask:0xf
	v_pk_add_f32 v[108:109], v[108:109], v[110:111]
	v_mov_b32_e32 v111, v121
	v_mov_b32_e32 v110, v121
	s_nop 0
	v_mov_b32_dpp v111, v109 row_ror:4 row_mask:0xf bank_mask:0xf
	v_mov_b32_dpp v110, v108 row_ror:4 row_mask:0xf bank_mask:0xf
	v_pk_add_f32 v[108:109], v[108:109], v[110:111]
	v_mov_b32_e32 v111, v121
	v_mov_b32_e32 v110, v121
	s_nop 0
	v_mov_b32_dpp v111, v109 row_ror:2 row_mask:0xf bank_mask:0xf
	v_mov_b32_dpp v110, v108 row_ror:2 row_mask:0xf bank_mask:0xf
	v_pk_add_f32 v[108:109], v[108:109], v[110:111]
	v_mov_b32_e32 v111, v121
	v_mov_b32_e32 v110, v121
	s_nop 0
	v_mov_b32_dpp v111, v109 row_ror:1 row_mask:0xf bank_mask:0xf
	v_mov_b32_dpp v110, v108 row_ror:1 row_mask:0xf bank_mask:0xf
	v_pk_add_f32 v[108:109], v[108:109], v[110:111]
	v_lshlrev_b32_e32 v111, 16, v169
	v_pk_fma_f32 v[108:109], v[108:109], s[16:17], v[106:107] op_sel_hi:[1,0,0]
	s_nop 0
	v_mul_f32_e32 v110, 0x4b800000, v109
	v_cmp_gt_f32_e32 vcc, s38, v109
	s_nop 1
	v_cndmask_b32_e32 v109, v109, v110, vcc
	v_rsq_f32_e32 v109, v109
	v_or_b32_e32 v110, s39, v154
	v_mul_f32_e32 v113, 0x45800000, v109
	v_cndmask_b32_e32 v109, v109, v113, vcc
	v_mul_f32_e32 v102, v102, v109
	v_fma_f32 v102, v129, v102, v145
	v_fmac_f32_e32 v102, v119, v120
	v_mul_f32_e32 v88, v88, v102
	v_cvt_pk_bf16_f32 v88, v88, s0
	global_store_short v[104:105], v88, off
	v_mul_f32_e32 v88, v103, v109
	v_fma_f32 v88, v142, v88, v146
	v_fmac_f32_e32 v88, v119, v168
	v_mul_f32_e32 v88, v92, v88
	v_cvt_pk_bf16_f32 v88, v88, s0
	global_store_short v[104:105], v88, off offset:32
	v_mul_f32_e32 v88, v101, v109
	v_fma_f32 v88, v143, v88, v147
	v_fmac_f32_e32 v88, v119, v111
	v_mul_f32_e32 v84, v84, v88
	v_cvt_pk_bf16_f32 v84, v84, s0
	global_store_short v[104:105], v84, off offset:64
	v_mul_f32_e32 v84, v100, v109
	v_fma_f32 v84, v144, v84, v148
	v_fmac_f32_e32 v84, v119, v112
	v_mul_f32_e32 v80, v80, v84
	v_ashrrev_i32_e32 v111, 31, v110
	v_cvt_pk_bf16_f32 v80, v80, s0
	v_lshlrev_b64 v[100:101], 6, v[110:111]
	global_store_short v[104:105], v80, off offset:96
	v_lshl_add_u64 v[100:101], v[130:131], 0, v[100:101]
	v_mul_f32_e32 v80, 0x4b800000, v108
	v_cmp_gt_f32_e32 vcc, s38, v108
	v_lshlrev_b32_e32 v88, 16, v171
	v_lshlrev_b64 v[102:103], 11, v[110:111]
	v_cndmask_b32_e32 v80, v108, v80, vcc
	v_rsq_f32_e32 v80, v80
	s_nop 0
	v_mul_f32_e32 v84, 0x45800000, v80
	v_cndmask_b32_e32 v80, v80, v84, vcc
	v_mul_f32_e32 v92, v98, v80
	v_fma_f32 v92, v129, v92, v145
	v_add_u32_e32 v98, 0xcc00, v162
	s_waitcnt vmcnt(9)
; __device__ __forceinline__ float bf2f(bf16_t b) { return __uint_as_float(((unsigned)b) << 16); }
; __device__ __forceinline__ void post_phase(PREF p, char* smem, const int wid_u, const int tile_first, const int tile_end, const int tile_step) {
;     ...
; #pragma unroll
;     for (int mt = 0; mt < 2; ++mt)
; #pragma unroll
;       for (int jj = 0; jj < 4; ++jj) {
;         const int tok = mt * 16 + fq * 4 + jj, row = row0 + tok;
;         float yv[4], sm_ = 0.f;
; #pragma unroll
;         for (int nt = 0; nt < 4; ++nt) { yv[nt] = ys[tok * 516 + w * 64 + nt * 16 + fr]; sm_ += yv[nt]; }
;         const float mean = row16_sum(sm_) * (1.f / 64.f);
;         float vs = 0.f;
; #pragma unroll
;         for (int nt = 0; nt < 4; ++nt) { yv[nt] -= mean; vs += yv[nt] * yv[nt]; }
;         const float rs = rsqrtf(row16_sum(vs) * (1.f / 64.f) + 64e-5f);
;         const float2 sb2 = *(const float2*)(P_SBON + ((size_t)row * 8 + w) * 2);
;         const float sbs = sb2.x + sb2.y;
; #pragma unroll
;         for (int nt = 0; nt < 4; ++nt) {
;           const float vv = bf2f(vt[tok * 520 + w * 64 + nt * 16 + fr]);
;           const float o = (yv[nt] * rs * lng[nt] + lnb[nt] + sbs * vv) * acc[mt][nt][jj];
;           mo[(size_t)row * D + 512 + w * 64 + nt * 16 + fr] = (bf16_t)(cvt_pk_bf16(o, 0.f) & 0xffff);
;         }
;       }
	v_add_f32_e32 v84, v252, v253
	global_load_dwordx2 v[252:253], v[250:251], off offset:1216
	v_fmac_f32_e32 v92, v84, v88
	v_mul_f32_e32 v88, v89, v92
	v_lshl_add_u64 v[100:101], v[132:133], 0, v[102:103]
	v_cvt_pk_bf16_f32 v88, v88, s0
	v_mul_f32_e32 v89, v99, v80
	global_store_short v[100:101], v88, off
	v_lshlrev_b32_e32 v88, 16, v172
	v_fma_f32 v89, v142, v89, v146
	v_fmac_f32_e32 v89, v84, v88
	v_mul_f32_e32 v88, v93, v89
	v_cvt_pk_bf16_f32 v88, v88, s0
	v_mul_f32_e32 v89, v97, v80
	global_store_short v[100:101], v88, off offset:32
	v_lshlrev_b32_e32 v88, 16, v173
	v_fma_f32 v89, v143, v89, v147
	v_fmac_f32_e32 v89, v84, v88
	v_mul_f32_e32 v85, v85, v89
	v_cvt_pk_bf16_f32 v85, v85, s0
	v_mul_f32_e32 v80, v96, v80
	global_store_short v[100:101], v85, off offset:64
	v_lshlrev_b32_e32 v85, 16, v174
	v_fma_f32 v80, v144, v80, v148
	v_fmac_f32_e32 v80, v84, v85
	v_mul_f32_e32 v80, v81, v80
	v_cvt_pk_bf16_f32 v80, v80, s0
	global_store_short v[100:101], v80, off offset:96
	v_or_b32_e32 v80, s39, v155
	v_ashrrev_i32_e32 v81, 31, v80
	v_lshlrev_b64 v[84:85], 6, v[80:81]
	v_lshl_add_u64 v[84:85], v[130:131], 0, v[84:85]
	v_add_u32_e32 v92, 0xc400, v162
	ds_read_u16 v100, v161 offset:30480
	ds_read_u16 v101, v161 offset:30512
	ds_read_u16 v112, v161 offset:30544
	ds_read_u16 v113, v161 offset:30576
	ds_read_u16 v114, v161 offset:31520
	ds_read_u16 v115, v161 offset:31552
	ds_read_u16 v116, v161 offset:31584
	ds_read_u16 v117, v161 offset:31616
	ds_read2_b32 v[88:89], v92 offset0:8 offset1:24
	ds_read2_b32 v[92:93], v92 offset0:40 offset1:56
	ds_read2_b32 v[96:97], v98 offset0:12 offset1:28
	ds_read2_b32 v[98:99], v98 offset0:44 offset1:60
	s_waitcnt lgkmcnt(10)
	v_lshlrev_b32_e32 v119, 16, v101
	s_waitcnt lgkmcnt(3)
	v_add_f32_e32 v104, 0, v88
	v_add_f32_e32 v104, v104, v89
	s_waitcnt lgkmcnt(1)
	v_add_f32_e32 v105, 0, v96
	v_add_f32_e32 v105, v105, v97
	v_mov_b32_e32 v101, v92
	s_waitcnt lgkmcnt(0)
	v_mov_b32_e32 v103, v98
	v_add_f32_e32 v92, v104, v92
	v_add_f32_e32 v98, v105, v98
	v_lshlrev_b32_e32 v118, 16, v100
	v_mov_b32_e32 v100, v93
	v_add_f32_e32 v92, v92, v93
	v_add_f32_e32 v93, v98, v99
	v_mov_b32_e32 v102, v99
	v_add_f32_dpp v92, v92, v92 row_ror:8 row_mask:0xf bank_mask:0xf bound_ctrl:1
	v_add_f32_dpp v93, v93, v93 row_ror:8 row_mask:0xf bank_mask:0xf bound_ctrl:1
	v_lshlrev_b64 v[80:81], 11, v[80:81]
	v_add_f32_dpp v92, v92, v92 row_ror:4 row_mask:0xf bank_mask:0xf bound_ctrl:1
	v_add_f32_dpp v93, v93, v93 row_ror:4 row_mask:0xf bank_mask:0xf bound_ctrl:1
	v_lshl_add_u64 v[80:81], v[132:133], 0, v[80:81]
	v_add_f32_dpp v92, v92, v92 row_ror:2 row_mask:0xf bank_mask:0xf bound_ctrl:1
	v_add_f32_dpp v93, v93, v93 row_ror:2 row_mask:0xf bank_mask:0xf bound_ctrl:1
	s_nop 0
	v_add_f32_dpp v92, v92, v92 row_ror:1 row_mask:0xf bank_mask:0xf bound_ctrl:1
	v_add_f32_dpp v93, v93, v93 row_ror:1 row_mask:0xf bank_mask:0xf bound_ctrl:1
	v_mul_f32_e32 v92, 0x3c800000, v92
	v_mul_f32_e32 v98, 0x3c800000, v93
	v_pk_add_f32 v[88:89], v[88:89], v[92:93] op_sel_hi:[1,0] neg_lo:[0,1] neg_hi:[0,1]
	v_pk_add_f32 v[96:97], v[96:97], v[98:99] op_sel_hi:[1,0] neg_lo:[0,1] neg_hi:[0,1]
	v_pk_add_f32 v[92:93], v[100:101], v[92:93] op_sel_hi:[1,0] neg_lo:[0,1] neg_hi:[0,1]
	v_pk_add_f32 v[98:99], v[102:103], v[98:99] op_sel_hi:[1,0] neg_lo:[0,1] neg_hi:[0,1]
	v_pk_mul_f32 v[100:101], v[88:89], v[88:89]
	v_pk_mul_f32 v[104:105], v[96:97], v[96:97]
	v_pk_mul_f32 v[102:103], v[92:93], v[92:93]
	v_pk_mul_f32 v[108:109], v[98:99], v[98:99]
	v_mov_b32_e32 v110, v104
	v_mov_b32_e32 v111, v100
	v_mov_b32_e32 v100, v105
	s_waitcnt vmcnt(9)
; __device__ __forceinline__ void post_phase(PREF p, char* smem, const int wid_u, const int tile_first, const int tile_end, const int tile_step) {
;     ...
;   for (int tile = tile_first; tile < tile_end; tile += tile_step) {
;     const int row0 = tile * 32;
;     int s, t0, T;
;     row_seq(row0, s, t0, T);
;     ...
;       }
;     __syncthreads();
;   }
	v_add_f32_e32 v104, v254, v255
	v_pk_add_f32 v[84:85], v[110:111], v[100:101]
	v_mov_b32_e32 v100, v109
	v_mov_b32_e32 v101, v103
	v_pk_add_f32 v[84:85], v[100:101], v[84:85]
	v_mov_b32_e32 v109, v102
	v_pk_add_f32 v[84:85], v[108:109], v[84:85]
	v_mov_b32_e32 v101, v121
	v_mov_b32_e32 v100, v121
	v_lshlrev_b32_e32 v102, 16, v113
	v_mov_b32_dpp v101, v85 row_ror:8 row_mask:0xf bank_mask:0xf
	v_mov_b32_dpp v100, v84 row_ror:8 row_mask:0xf bank_mask:0xf
	v_pk_add_f32 v[84:85], v[84:85], v[100:101]
	v_mov_b32_e32 v101, v121
	v_mov_b32_e32 v100, v121
	s_nop 0
	v_mov_b32_dpp v101, v85 row_ror:4 row_mask:0xf bank_mask:0xf
	v_mov_b32_dpp v100, v84 row_ror:4 row_mask:0xf bank_mask:0xf
	v_pk_add_f32 v[84:85], v[84:85], v[100:101]
	v_mov_b32_e32 v101, v121
	v_mov_b32_e32 v100, v121
	s_nop 0
	v_mov_b32_dpp v101, v85 row_ror:2 row_mask:0xf bank_mask:0xf
	v_mov_b32_dpp v100, v84 row_ror:2 row_mask:0xf bank_mask:0xf
	v_pk_add_f32 v[84:85], v[84:85], v[100:101]
	v_mov_b32_e32 v101, v121
	v_mov_b32_e32 v100, v121
	s_nop 0
	v_mov_b32_dpp v101, v85 row_ror:1 row_mask:0xf bank_mask:0xf
	v_mov_b32_dpp v100, v84 row_ror:1 row_mask:0xf bank_mask:0xf
	v_pk_add_f32 v[84:85], v[84:85], v[100:101]
	v_lshlrev_b32_e32 v101, 16, v112
	v_pk_fma_f32 v[84:85], v[84:85], s[16:17], v[106:107] op_sel_hi:[1,0,0]
	v_mul_f32_e32 v100, 0x4b800000, v85
	v_cmp_gt_f32_e32 vcc, s38, v85
	s_nop 0
	v_cndmask_b32_e32 v85, v85, v100, vcc
	v_rsq_f32_e32 v85, v85
	v_or_b32_e32 v100, s39, v156
	v_mul_f32_e32 v103, 0x45800000, v85
	v_cndmask_b32_e32 v85, v85, v103, vcc
	v_mul_f32_e32 v88, v88, v85
	v_fma_f32 v88, v129, v88, v145
	v_fmac_f32_e32 v88, v104, v118
	v_mul_f32_e32 v88, v90, v88
	v_cvt_pk_bf16_f32 v88, v88, s0
	global_store_short v[80:81], v88, off
	v_mul_f32_e32 v88, v89, v85
	v_fma_f32 v88, v142, v88, v146
	v_fmac_f32_e32 v88, v104, v119
	v_mul_f32_e32 v88, v94, v88
	v_cvt_pk_bf16_f32 v88, v88, s0
	global_store_short v[80:81], v88, off offset:32
	v_mul_f32_e32 v88, v93, v85
	v_mul_f32_e32 v85, v92, v85
	v_fma_f32 v88, v143, v88, v147
	v_fma_f32 v85, v144, v85, v148
	v_fmac_f32_e32 v88, v104, v101
	v_fmac_f32_e32 v85, v104, v102
	v_mul_f32_e32 v86, v86, v88
	v_mul_f32_e32 v82, v82, v85
	v_cvt_pk_bf16_f32 v86, v86, s0
	v_cvt_pk_bf16_f32 v82, v82, s0
	v_ashrrev_i32_e32 v101, 31, v100
	global_store_short v[80:81], v86, off offset:64
	global_store_short v[80:81], v82, off offset:96
	v_lshlrev_b64 v[80:81], 6, v[100:101]
	v_lshl_add_u64 v[80:81], v[130:131], 0, v[80:81]
	v_mul_f32_e32 v82, 0x4b800000, v84
	v_cmp_gt_f32_e32 vcc, s38, v84
	v_lshlrev_b32_e32 v85, 16, v115
	v_lshlrev_b64 v[88:89], 11, v[100:101]
	v_cndmask_b32_e32 v82, v84, v82, vcc
	v_rsq_f32_e32 v82, v82
	v_lshlrev_b32_e32 v84, 16, v114
	v_lshl_add_u64 v[88:89], v[132:133], 0, v[88:89]
	v_lshlrev_b32_e32 v86, 16, v116
	v_mul_f32_e32 v90, 0x45800000, v82
	v_cndmask_b32_e32 v82, v82, v90, vcc
	v_mul_f32_e32 v90, v96, v82
	v_mul_f32_e32 v92, v97, v82
	v_fma_f32 v90, v129, v90, v145
	v_fma_f32 v92, v142, v92, v146
	s_waitcnt vmcnt(8)
	v_add_f32_e32 v80, v252, v253
	v_fmac_f32_e32 v90, v80, v84
	v_fmac_f32_e32 v92, v80, v85
	v_mul_f32_e32 v81, v91, v90
	v_mul_f32_e32 v84, v95, v92
	v_cvt_pk_bf16_f32 v81, v81, s0
	v_cvt_pk_bf16_f32 v84, v84, s0
	global_store_short v[88:89], v81, off
	global_store_short v[88:89], v84, off offset:32
	v_mul_f32_e32 v81, v99, v82
	v_fma_f32 v81, v143, v81, v147
	v_fmac_f32_e32 v81, v80, v86
	v_mul_f32_e32 v81, v87, v81
	v_cvt_pk_bf16_f32 v81, v81, s0
	v_mul_f32_e32 v82, v98, v82
	global_store_short v[88:89], v81, off offset:64
	v_lshlrev_b32_e32 v81, 16, v117
	v_fma_f32 v82, v144, v82, v148
	v_fmac_f32_e32 v82, v80, v81
	v_mul_f32_e32 v80, v83, v82
	v_cvt_pk_bf16_f32 v80, v80, s0
	global_store_short v[88:89], v80, off offset:96
	s_barrier
.LBB0_827:
	s_cmp_lg_u32 s84, 0
	s_cbranch_scc1 .Lpop_join
	s_mov_b64 exec, 1
	v_mov_b32_e32 v250, 0
	v_mov_b32_e32 v251, 1
	global_atomic_add v250, v250, v251, s[100:101] offset:256 sc0
	s_waitcnt vmcnt(0)
	v_readfirstlane_b32 s98, v250
	s_mov_b64 exec, -1
	s_cmp_ge_u32 s98, 0x800
	s_cbranch_scc1 .Lpop_done
	s_and_b32 s99, s98, 7
	s_lshr_b32 s98, s98, 3
	s_lshr_b32 s17, s98, 1
	s_bitcmp1_b32 s98, 0
	s_cbranch_scc1 .Lpop_odd
	s_add_i32 s17, s17, 0x80
	s_branch .Lpop_q
.Lpop_odd:
	s_sub_i32 s17, 0x7f, s17
.Lpop_q:
	s_add_i32 s98, s17, 1
	v_mov_b32_e32 v251, s98
	s_sub_i32 s98, 0x100, s17
	v_mov_b32_e32 v252, s98
	v_mbcnt_lo_u32_b32 v250, -1, 0
	v_mbcnt_hi_u32_b32 v250, -1, v250
	v_and_b32_e32 v253, 1, v250
	v_cmp_eq_u32_e32 vcc, 1, v253
	v_and_b32_e32 v250, 15, v250
	v_cndmask_b32_e32 v251, v251, v252, vcc
	v_lshlrev_b32_e32 v250, 2, v250
	s_lshl_b32 s98, s99, 8
	s_add_i32 s98, s98, 0x440
	v_add_u32_e32 v250, s98, v250
	s_lshl_b32 s99, s99, 8
	s_add_i32 s17, s17, s99
	s_add_i32 s17, s17, 0x400
	s_mov_b32 s99, 0
.Lpop_poll:
	global_load_dword v252, v250, s[100:101] sc0 sc1
	s_waitcnt vmcnt(0)
	v_cmp_lt_u32_e32 vcc, v252, v251
	s_cbranch_vccz .Lpop_ready
	s_sleep 8
	s_add_i32 s99, s99, 1
	s_cmp_lt_u32 s99, 0x2000
	s_cbranch_scc1 .Lpop_poll
.Lpop_ready:
	buffer_inv sc1
	s_waitcnt vmcnt(0)
	s_branch .Lpop_bcast
.Lpop_done:
	s_movk_i32 s17, 0xc00
.Lpop_bcast:
	v_mov_b32_e32 v250, 0x27900
	v_mov_b32_e32 v251, s17
	ds_write_b32 v250, v251
	s_waitcnt lgkmcnt(0)
.Lpop_join:
	s_barrier
	v_mov_b32_e32 v250, 0x27900
	ds_read_b32 v250, v250
	s_waitcnt lgkmcnt(0)
	v_readfirstlane_b32 s17, v250
	s_cmp_ge_i32 s17, 0xc00
	s_cbranch_scc1 .LBB0_846
	s_lshl_b32 s39, s17, 5
	s_cmpk_lt_i32 s17, 0x400
	s_cselect_b32 s20, s29, 0x1fe0
	s_cselect_b32 s40, s30, 0x1fff
	s_and_b32 s41, s20, s39
	s_and_saveexec_b64 s[20:21], s[2:3]
	s_cbranch_execz .LBB0_836
	v_lshl_add_u32 v93, v127, 4, 0
	s_mov_b64 s[22:23], 0
	v_mov_b32_e32 v92, v163
	v_mov_b32_e32 v94, v127
	s_branch .LBB0_831

; __global__ void __launch_bounds__(NTHR, 2) mega_kernel(Params p) {
	.amdhsa_kernel _Z11mega_kernel6Params
		.amdhsa_group_segment_fixed_size 0
		.amdhsa_private_segment_fixed_size 0
		.amdhsa_kernarg_size 536
		.amdhsa_user_sgpr_count 2
		.amdhsa_user_sgpr_dispatch_ptr 0
		.amdhsa_user_sgpr_queue_ptr 0
		.amdhsa_user_sgpr_kernarg_segment_ptr 1
		.amdhsa_user_sgpr_dispatch_id 0
		.amdhsa_user_sgpr_kernarg_preload_length 0
		.amdhsa_user_sgpr_kernarg_preload_offset 0
		.amdhsa_user_sgpr_private_segment_size 0
		.amdhsa_uses_dynamic_stack 0
		.amdhsa_enable_private_segment 0
		.amdhsa_system_sgpr_workgroup_id_x 1
		.amdhsa_system_sgpr_workgroup_id_y 0
		.amdhsa_system_sgpr_workgroup_id_z 0
		.amdhsa_system_sgpr_workgroup_info 0
		.amdhsa_system_vgpr_workitem_id 2
		.amdhsa_next_free_vgpr 256
		.amdhsa_next_free_sgpr 102
		.amdhsa_accum_offset 256
		.amdhsa_reserve_vcc 1
		.amdhsa_float_round_mode_32 0
		.amdhsa_float_round_mode_16_64 0
		.amdhsa_float_denorm_mode_32 3
		.amdhsa_float_denorm_mode_16_64 3
		.amdhsa_dx10_clamp 1
		.amdhsa_ieee_mode 1
		.amdhsa_fp16_overflow 0
		.amdhsa_tg_split 0
		.amdhsa_exception_fp_ieee_invalid_op 0
		.amdhsa_exception_fp_denorm_src 0
		.amdhsa_exception_fp_ieee_div_zero 0
		.amdhsa_exception_fp_ieee_overflow 0
		.amdhsa_exception_fp_ieee_underflow 0
		.amdhsa_exception_fp_ieee_inexact 0
		.amdhsa_exception_int_div_zero 0
	.end_amdhsa_kernel

; #define LAS __attribute__((address_space(3)))
; __device__ __forceinline__ unsigned xb_add(unsigned* p, unsigned v) { return __hip_atomic_fetch_add(p, v, __ATOMIC_RELAXED, __HIP_MEMORY_SCOPE_AGENT); }
; __device__ __forceinline__ unsigned xb_xcc_id() { return (unsigned)__builtin_amdgcn_s_getreg((3 << 11) | 20) & 0xFu; }
; #define RUN_PHASE(PH) do { KP kp = kp0; asm volatile("" : "+s"(kp)); do_phase(*kp, PH, dyn_smem, wid_u); \
;     if (PH == 0) grid.sync(); \
;     else if (PH + 1 < NPHASE) xcd_barrier(*kp, (volatile LAS unsigned*)((LAS char*)dyn_smem + (SMEM_BYTES - 16)), wid_u); } while (0)
; __global__ void __launch_bounds__(NTHR, 2) mega_kernel(Params p) {
;   cg::grid_group grid = cg::this_grid();
;   const int wid_u = __builtin_amdgcn_readfirstlane(threadIdx.x >> 6);
;   typedef const __attribute__((address_space(4))) Params* KP;
;   const KP kp0 = (KP)__builtin_amdgcn_kernarg_segment_ptr();
;   volatile LAS unsigned* st = (volatile LAS unsigned*)((LAS char*)dyn_smem + (SMEM_BYTES - 16));
;   if (threadIdx.x < 2) st[threadIdx.x] = 0u;
;   __syncthreads();
;   if (threadIdx.x == 0) (void)xb_add(&((unsigned*)(kp0->ws + OFF_BAR))[XB_XCNT(xb_xcc_id())], 1u);
;     ...
;   RUN_PHASE(0); RUN_PHASE(1); RUN_PHASE(2); RUN_PHASE(3); RUN_PHASE(4); RUN_PHASE(5); RUN_PHASE(6);
;   RUN_PHASE(7); RUN_PHASE(8); RUN_PHASE(9); RUN_PHASE(10); RUN_PHASE(11); RUN_PHASE(12); RUN_PHASE(13);
;     ...
; }
; __global__ void __launch_bounds__(NTHR, 2) phase_kernel(Params p, int ph) {
;   const int wid_u = __builtin_amdgcn_readfirstlane(threadIdx.x >> 6);
;   do_phase(*(const __attribute__((address_space(4))) Params*)__builtin_amdgcn_kernarg_segment_ptr(), ph, dyn_smem, wid_u);
; }
amdhsa.kernels:
  - .agpr_count:     0
    .args:
      - .offset:         0
        .size:           280
        .value_kind:     by_value
      - .offset:         280
        .size:           4
        .value_kind:     hidden_block_count_x
      - .offset:         284
        .size:           4
        .value_kind:     hidden_block_count_y
      - .offset:         288
        .size:           4
        .value_kind:     hidden_block_count_z
      - .offset:         292
        .size:           2
        .value_kind:     hidden_group_size_x
      - .offset:         294
        .size:           2
        .value_kind:     hidden_group_size_y
      - .offset:         296
        .size:           2
        .value_kind:     hidden_group_size_z
      - .offset:         298
        .size:           2
        .value_kind:     hidden_remainder_x
      - .offset:         300
        .size:           2
        .value_kind:     hidden_remainder_y
      - .offset:         302
        .size:           2
        .value_kind:     hidden_remainder_z
      - .offset:         320
        .size:           8
        .value_kind:     hidden_global_offset_x
      - .offset:         328
        .size:           8
        .value_kind:     hidden_global_offset_y
      - .offset:         336
        .size:           8
        .value_kind:     hidden_global_offset_z
      - .offset:         344
        .size:           2
        .value_kind:     hidden_grid_dims
      - .offset:         368
        .size:           8
        .value_kind:     hidden_multigrid_sync_arg
      - .offset:         400
        .size:           4
        .value_kind:     hidden_dynamic_lds_size
    .group_segment_fixed_size: 0
    .kernarg_segment_align: 8
    .kernarg_segment_size: 536
    .language:       OpenCL C
    .language_version:
      - 2
      - 0
    .max_flat_workgroup_size: 512
    .name:           _Z11mega_kernel6Params
    .private_segment_fixed_size: 0
    .sgpr_count:     108
    .sgpr_spill_count: 7
    .symbol:         _Z11mega_kernel6Params.kd
    .uniform_work_group_size: 1
    .uses_dynamic_stack: false
    .vgpr_count:     256
    .vgpr_spill_count: 0
    .wavefront_size: 64
  - .agpr_count:     0
    .args:
      - .offset:         0
        .size:           280
        .value_kind:     by_value
      - .offset:         280
        .size:           4
        .value_kind:     by_value
      - .offset:         288
        .size:           4
        .value_kind:     hidden_block_count_x
      - .offset:         292
        .size:           4
        .value_kind:     hidden_block_count_y
      - .offset:         296
        .size:           4
        .value_kind:     hidden_block_count_z
      - .offset:         300
        .size:           2
        .value_kind:     hidden_group_size_x
      - .offset:         302
        .size:           2
        .value_kind:     hidden_group_size_y
      - .offset:         304
        .size:           2
        .value_kind:     hidden_group_size_z
      - .offset:         306
        .size:           2
        .value_kind:     hidden_remainder_x
      - .offset:         308
        .size:           2
        .value_kind:     hidden_remainder_y
      - .offset:         310
        .size:           2
        .value_kind:     hidden_remainder_z
      - .offset:         328
        .size:           8
        .value_kind:     hidden_global_offset_x
      - .offset:         336
        .size:           8
        .value_kind:     hidden_global_offset_y
      - .offset:         344
        .size:           8
        .value_kind:     hidden_global_offset_z
      - .offset:         352
        .size:           2
        .value_kind:     hidden_grid_dims
      - .offset:         408
        .size:           4
        .value_kind:     hidden_dynamic_lds_size
    .group_segment_fixed_size: 0
    .kernarg_segment_align: 8
    .kernarg_segment_size: 544
    .language:       OpenCL C
    .language_version:
      - 2
      - 0
    .max_flat_workgroup_size: 512
    .name:           _Z12phase_kernel6Paramsi
    .private_segment_fixed_size: 0
    .sgpr_count:     106
    .sgpr_spill_count: 0
    .symbol:         _Z12phase_kernel6Paramsi.kd
    .uniform_work_group_size: 1
    .uses_dynamic_stack: false
    .vgpr_count:     254
    .vgpr_spill_count: 0
    .wavefront_size: 64
